# adds packed-fma exp prescale in attention loop and 16-byte epilogue stores (permlane16_swap pairing) in up-projection and in-projection plain path
# speedup vs baseline: 1.0481x; 1.0143x over previous
.LBB0_115:
	v_and_b32_e32 v254, 1, v142
	v_mul_u32_u24_e32 v254, 24, v254
	v_mov_b32_e32 v255, 0
	v_or_b32_e32 v128, s6, v144
	s_movk_i32 s4, 0xd80
	v_cmp_gt_i32_e32 vcc, s4, v128
	s_and_saveexec_b64 s[6:7], vcc
	s_cbranch_execz .LBB0_101
	v_or_b32_e32 v129, s46, v143
	v_mov_b64_e32 v[130:131], v[132:133]
	v_add_u32_e32 v148, v129, v134
	v_ashrrev_i32_e32 v129, 31, v128
	v_mad_i64_i32 v[130:131], s[46:47], v148, s50, v[130:131]
	v_lshl_add_u64 v[130:131], v[128:129], 1, v[130:131]
	v_lshlrev_b32_e32 v134, 3, v142
	s_movk_i32 s4, 0x3ff
	v_lshl_add_u64 v[130:131], v[130:131], 0, v[134:135]
	v_cmp_lt_i32_e64 s[4:5], s4, v128
	v_lshl_add_u64 v[138:139], v[130:131], 0, s[22:23]
	s_and_saveexec_b64 s[46:47], s[4:5]
	s_xor_b64 s[46:47], exec, s[46:47]
	s_cbranch_execz .LBB0_118
	v_lshl_add_u64 v[252:253], v[138:139], 0, v[254:255]
	v_cvt_pk_bf16_f32 v120, v120, v121
	v_cvt_pk_bf16_f32 v121, v122, v123
	v_cvt_pk_bf16_f32 v122, v112, v113
	v_cvt_pk_bf16_f32 v123, v114, v115
	s_nop 1
	v_permlane16_swap_b32_e32 v120, v122
	v_permlane16_swap_b32_e32 v121, v123
	global_store_dwordx4 v[252:253], v[120:123], off
	s_nop 1
	v_cvt_pk_bf16_f32 v124, v124, v125
	v_cvt_pk_bf16_f32 v125, v126, v127
	v_cvt_pk_bf16_f32 v126, v116, v117
	v_cvt_pk_bf16_f32 v127, v118, v119
	s_nop 1
	v_permlane16_swap_b32_e32 v124, v126
	v_permlane16_swap_b32_e32 v125, v127
	global_store_dwordx4 v[252:253], v[124:127], off offset:64
	s_nop 1
	v_cvt_pk_bf16_f32 v104, v104, v105
	v_cvt_pk_bf16_f32 v105, v106, v107
	v_cvt_pk_bf16_f32 v106, v96, v97
	v_cvt_pk_bf16_f32 v107, v98, v99
	s_nop 1
	v_permlane16_swap_b32_e32 v104, v106
	v_permlane16_swap_b32_e32 v105, v107
	global_store_dwordx4 v[252:253], v[104:107], off offset:128
	s_nop 1
	v_cvt_pk_bf16_f32 v140, v100, v101
	v_cvt_pk_bf16_f32 v141, v102, v103
	v_cvt_pk_bf16_f32 v108, v108, v109
	v_cvt_pk_bf16_f32 v109, v110, v111
	v_cvt_pk_bf16_f32 v110, v100, v101
	v_cvt_pk_bf16_f32 v111, v102, v103
	s_nop 1
	v_permlane16_swap_b32_e32 v108, v110
	v_permlane16_swap_b32_e32 v109, v111
	global_store_dwordx4 v[252:253], v[108:111], off offset:192
	s_nop 1

.LBB0_120:
	s_or_b64 exec, exec, s[46:47]
	v_mov_b64_e32 v[96:97], v[132:133]
	global_store_dwordx2 v[138:139], v[140:141], off offset:224
	v_or_b32_e32 v100, 16, v148
	v_lshlrev_b32_e32 v134, 1, v149
	v_mad_i64_i32 v[96:97], s[46:47], v100, s50, v[96:97]
	v_lshl_add_u64 v[96:97], v[128:129], 1, v[96:97]
	v_lshl_add_u64 v[96:97], v[96:97], 0, v[134:135]
	v_lshl_add_u64 v[96:97], v[96:97], 0, s[22:23]
	s_and_saveexec_b64 s[46:47], s[4:5]
	s_xor_b64 s[46:47], exec, s[46:47]
	s_cbranch_execz .LBB0_122
	v_lshl_add_u64 v[252:253], v[96:97], 0, v[254:255]
	v_cvt_pk_bf16_f32 v88, v88, v89
	v_cvt_pk_bf16_f32 v89, v90, v91
	v_cvt_pk_bf16_f32 v90, v80, v81
	v_cvt_pk_bf16_f32 v91, v82, v83
	s_nop 1
	v_permlane16_swap_b32_e32 v88, v90
	v_permlane16_swap_b32_e32 v89, v91
	global_store_dwordx4 v[252:253], v[88:91], off
	s_nop 1
	v_cvt_pk_bf16_f32 v92, v92, v93
	v_cvt_pk_bf16_f32 v93, v94, v95
	v_cvt_pk_bf16_f32 v94, v84, v85
	v_cvt_pk_bf16_f32 v95, v86, v87
	s_nop 1
	v_permlane16_swap_b32_e32 v92, v94
	v_permlane16_swap_b32_e32 v93, v95
	global_store_dwordx4 v[252:253], v[92:95], off offset:64
	s_nop 1
	v_cvt_pk_bf16_f32 v72, v72, v73
	v_cvt_pk_bf16_f32 v73, v74, v75
	v_cvt_pk_bf16_f32 v74, v64, v65
	v_cvt_pk_bf16_f32 v75, v66, v67
	s_nop 1
	v_permlane16_swap_b32_e32 v72, v74
	v_permlane16_swap_b32_e32 v73, v75
	global_store_dwordx4 v[252:253], v[72:75], off offset:128
	s_nop 1
	v_cvt_pk_bf16_f32 v98, v68, v69
	v_cvt_pk_bf16_f32 v99, v70, v71
	v_cvt_pk_bf16_f32 v76, v76, v77
	v_cvt_pk_bf16_f32 v77, v78, v79
	v_cvt_pk_bf16_f32 v78, v68, v69
	v_cvt_pk_bf16_f32 v79, v70, v71
	s_nop 1
	v_permlane16_swap_b32_e32 v76, v78
	v_permlane16_swap_b32_e32 v77, v79
	global_store_dwordx4 v[252:253], v[76:79], off offset:192
	s_nop 1

.LBB0_124:
	s_or_b64 exec, exec, s[46:47]
	v_mov_b64_e32 v[64:65], v[132:133]
	global_store_dwordx2 v[96:97], v[98:99], off offset:224
	v_or_b32_e32 v68, 32, v148
	s_nop 0
	v_mad_i64_i32 v[64:65], s[46:47], v68, s50, v[64:65]
	v_lshl_add_u64 v[64:65], v[128:129], 1, v[64:65]
	v_lshl_add_u64 v[64:65], v[64:65], 0, v[134:135]
	v_lshl_add_u64 v[64:65], v[64:65], 0, s[22:23]
	s_and_saveexec_b64 s[46:47], s[4:5]
	s_xor_b64 s[46:47], exec, s[46:47]
	s_cbranch_execz .LBB0_126
	v_lshl_add_u64 v[252:253], v[64:65], 0, v[254:255]
	v_cvt_pk_bf16_f32 v56, v56, v57
	v_cvt_pk_bf16_f32 v57, v58, v59
	v_cvt_pk_bf16_f32 v58, v48, v49
	v_cvt_pk_bf16_f32 v59, v50, v51
	s_nop 1
	v_permlane16_swap_b32_e32 v56, v58
	v_permlane16_swap_b32_e32 v57, v59
	global_store_dwordx4 v[252:253], v[56:59], off
	s_nop 1
	v_cvt_pk_bf16_f32 v60, v60, v61
	v_cvt_pk_bf16_f32 v61, v62, v63
	v_cvt_pk_bf16_f32 v62, v52, v53
	v_cvt_pk_bf16_f32 v63, v54, v55
	s_nop 1
	v_permlane16_swap_b32_e32 v60, v62
	v_permlane16_swap_b32_e32 v61, v63
	global_store_dwordx4 v[252:253], v[60:63], off offset:64
	s_nop 1
	v_cvt_pk_bf16_f32 v40, v40, v41
	v_cvt_pk_bf16_f32 v41, v42, v43
	v_cvt_pk_bf16_f32 v42, v32, v33
	v_cvt_pk_bf16_f32 v43, v34, v35
	s_nop 1
	v_permlane16_swap_b32_e32 v40, v42
	v_permlane16_swap_b32_e32 v41, v43
	global_store_dwordx4 v[252:253], v[40:43], off offset:128
	s_nop 1
	v_cvt_pk_bf16_f32 v66, v36, v37
	v_cvt_pk_bf16_f32 v67, v38, v39
	v_cvt_pk_bf16_f32 v44, v44, v45
	v_cvt_pk_bf16_f32 v45, v46, v47
	v_cvt_pk_bf16_f32 v46, v36, v37
	v_cvt_pk_bf16_f32 v47, v38, v39
	s_nop 1
	v_permlane16_swap_b32_e32 v44, v46
	v_permlane16_swap_b32_e32 v45, v47
	global_store_dwordx4 v[252:253], v[44:47], off offset:192
	s_nop 1

.LBB0_128:
	s_or_b64 exec, exec, s[46:47]
	v_mov_b64_e32 v[32:33], v[132:133]
	global_store_dwordx2 v[64:65], v[66:67], off offset:224
	v_or_b32_e32 v36, 48, v148
	s_nop 0
	v_mad_i64_i32 v[32:33], s[46:47], v36, s50, v[32:33]
	v_lshl_add_u64 v[32:33], v[128:129], 1, v[32:33]
	v_lshl_add_u64 v[32:33], v[32:33], 0, v[134:135]
	v_lshl_add_u64 v[32:33], v[32:33], 0, s[22:23]
	s_and_saveexec_b64 s[46:47], s[4:5]
	s_xor_b64 s[4:5], exec, s[46:47]
	s_cbranch_execz .LBB0_130
	v_lshl_add_u64 v[252:253], v[32:33], 0, v[254:255]
	v_cvt_pk_bf16_f32 v24, v24, v25
	v_cvt_pk_bf16_f32 v25, v26, v27
	v_cvt_pk_bf16_f32 v26, v16, v17
	v_cvt_pk_bf16_f32 v27, v18, v19
	s_nop 1
	v_permlane16_swap_b32_e32 v24, v26
	v_permlane16_swap_b32_e32 v25, v27
	global_store_dwordx4 v[252:253], v[24:27], off
	s_nop 1
	v_cvt_pk_bf16_f32 v28, v28, v29
	v_cvt_pk_bf16_f32 v29, v30, v31
	v_cvt_pk_bf16_f32 v30, v20, v21
	v_cvt_pk_bf16_f32 v31, v22, v23
	s_nop 1
	v_permlane16_swap_b32_e32 v28, v30
	v_permlane16_swap_b32_e32 v29, v31
	global_store_dwordx4 v[252:253], v[28:31], off offset:64
	s_nop 1
	v_cvt_pk_bf16_f32 v8, v8, v9
	v_cvt_pk_bf16_f32 v9, v10, v11
	v_cvt_pk_bf16_f32 v10, v0, v1
	v_cvt_pk_bf16_f32 v11, v2, v3
	s_nop 1
	v_permlane16_swap_b32_e32 v8, v10
	v_permlane16_swap_b32_e32 v9, v11
	global_store_dwordx4 v[252:253], v[8:11], off offset:128
	s_nop 1
	v_cvt_pk_bf16_f32 v34, v4, v5
	v_cvt_pk_bf16_f32 v35, v6, v7
	v_cvt_pk_bf16_f32 v12, v12, v13
	v_cvt_pk_bf16_f32 v13, v14, v15
	v_cvt_pk_bf16_f32 v14, v4, v5
	v_cvt_pk_bf16_f32 v15, v6, v7
	s_nop 1
	v_permlane16_swap_b32_e32 v12, v14
	v_permlane16_swap_b32_e32 v13, v15
	global_store_dwordx4 v[252:253], v[12:15], off offset:192
	s_nop 1

.LBB0_214:
	s_mov_b32 s100, 0x3e38aa3b
	s_mov_b32 s101, 0x3e38aa3b
	s_lshl_b32 s4, s15, 2
	s_and_b32 s4, s4, 8
	v_readlane_b32 s5, v249, 53
	s_or_b32 s5, s4, s5
	s_lshl_b32 s4, s15, 5
	s_and_b32 s4, s4, 32
	v_readlane_b32 s6, v249, 62
	s_add_i32 s4, s4, s6
	v_mov_b64_e32 v[0:1], v[132:133]
	s_lshr_b32 s6, s5, 2
	v_mov_b32_e32 v18, v154
	s_lshl_b32 s7, s5, 11
	s_ashr_i32 s5, s4, 31
	v_lshl_add_u64 v[140:141], v[0:1], 0, s[22:23]
	s_lshl_b64 s[4:5], s[4:5], 7
	v_ashrrev_i32_e32 v173, 7, v18
	v_and_b32_e32 v0, 0x3fffffc0, v18
	v_lshl_add_u32 v174, v0, 2, s79
	s_add_u32 s4, s7, s4
	v_lshlrev_b32_e32 v0, 5, v173
	s_addc_u32 s5, 0, s5
	v_ashrrev_i32_e32 v1, 31, v0
	v_and_b32_e32 v138, 31, v18
	v_lshl_add_u64 v[142:143], s[4:5], 0, v[0:1]
	v_or_b32_e32 v0, v142, v138
	v_mad_u64_u32 v[0:1], s[4:5], v0, s50, v[140:141]
	s_mul_i32 s52, s6, 0x3600000
	v_readlane_b32 s4, v249, 54
	v_bfe_u32 v172, v18, 6, 1
	v_lshl_add_u64 v[2:3], v[140:141], 0, s[52:53]
	v_mad_i32_i24 v1, v143, s50, v1
	s_lshl_b32 s52, s4, 1
	v_bfe_u32 v170, v18, 5, 1
	v_lshl_add_u64 v[0:1], v[0:1], 0, s[52:53]
	v_lshlrev_b32_e32 v134, 7, v172
	v_lshl_add_u64 v[0:1], v[0:1], 0, v[134:135]
	v_lshlrev_b32_e32 v144, 4, v170
	v_mov_b32_e32 v145, v135
	v_ashrrev_i32_e32 v19, 4, v18
	v_lshl_add_u64 v[0:1], v[0:1], 0, v[144:145]
	v_and_b32_e32 v4, 0xfffff0, v19
	v_lshlrev_b32_e32 v5, 1, v19
	global_load_dwordx4 v[108:111], v[0:1], off
	global_load_dwordx4 v[104:107], v[0:1], off offset:32
	global_load_dwordx4 v[100:103], v[0:1], off offset:64
	global_load_dwordx4 v[96:99], v[0:1], off offset:96
	v_lshlrev_b32_e32 v0, 3, v18
	v_and_or_b32 v4, v5, 8, v4
	v_lshrrev_b32_e32 v4, 1, v4
	v_bfe_u32 v6, v0, 5, 2
	v_and_b32_e32 v1, 0x78, v0
	v_or_b32_e32 v0, v4, v6
	v_lshrrev_b32_e32 v5, 1, v19
	v_lshlrev_b32_e32 v4, 9, v0
	v_and_b32_e32 v0, 3, v19
	v_and_or_b32 v0, v5, 4, v0
	v_add_u32_e32 v20, 32, v19
	v_lshlrev_b32_e32 v5, 6, v0
	v_lshlrev_b32_e32 v0, 1, v1
	v_and_b32_e32 v1, 0xfffff0, v20
	v_lshlrev_b32_e32 v7, 1, v20
	v_and_or_b32 v1, v7, 8, v1
	v_and_b32_e32 v171, 63, v18
	v_lshrrev_b32_e32 v1, 1, v1
	v_lshlrev_b32_e32 v7, 4, v18
	v_or_b32_e32 v1, v1, v6
	v_lshlrev_b32_e32 v6, 3, v171
	v_and_b32_e32 v8, 0xc0, v7
	v_lshlrev_b32_e32 v9, 1, v18
	v_and_or_b32 v8, v6, 24, v8
	v_and_b32_e32 v9, 32, v9
	v_and_b32_e32 v6, 0x100, v6
	v_or3_b32 v48, v8, v9, v6
	v_or_b32_e32 v8, v134, v144
	v_lshlrev_b32_e32 v6, 8, v138
	v_and_b32_e32 v7, 0x70, v7
	v_or_b32_e32 v9, 32, v8
	v_bitop3_b32 v21, v8, v6, v7 bitop3:0xde
	v_xad_u32 v50, v9, v7, v6
	v_or_b32_e32 v9, 64, v8
	v_or_b32_e32 v8, 0x60, v8
	v_lshlrev_b32_e32 v1, 9, v1
	v_xad_u32 v58, v9, v7, v6
	v_xad_u32 v49, v8, v7, v6
	v_lshl_add_u64 v[2:3], v[2:3], 0, s[52:53]
	v_and_b32_e32 v6, 48, v0
	v_or3_b32 v23, v1, v5, v6
	v_mad_i64_i32 v[2:3], s[4:5], v19, s50, v[2:3]
	v_mov_b32_e32 v1, v135
	v_lshl_add_u64 v[2:3], v[2:3], 0, v[0:1]
	s_mov_b64 s[4:5], 0x400
	v_lshl_add_u64 v[146:147], v[2:3], 0, s[4:5]
	s_mov_b64 s[4:5], 0x36400
	v_lshl_add_u64 v[148:149], v[2:3], 0, s[4:5]
	v_or3_b32 v22, v4, v5, v6
	global_load_dwordx4 v[2:5], v[146:147], off offset:1024
	global_load_dwordx4 v[6:9], v[148:149], off offset:1024
	global_load_dwordx4 v[10:13], v[146:147], off
	global_load_dwordx4 v[14:17], v[148:149], off
	v_add_u32_e32 v134, 0, v22
	s_waitcnt vmcnt(0)
	v_lshlrev_b32_e32 v1, 8, v19
	v_add_u32_e32 v145, 0, v23
	v_add_u32_e32 v181, 0, v21
	v_add_u32_e32 v182, 0, v50
	v_add_u32_e32 v183, 0, v58
	v_add_u32_e32 v184, 0, v49
	s_cmp_lg_u32 0, -1
	s_cselect_b32 s6, 0, 0
	s_mov_b32 s4, 0x6c000
	s_mov_b32 s57, s56
	s_mov_b32 s58, s56
	s_mov_b32 s59, s56
	s_mov_b32 s60, s56
	s_mov_b32 s61, s56
	s_mov_b32 s62, s56
	s_mov_b32 s63, s56
	s_mov_b32 s64, s56
	s_mov_b32 s65, s56
	s_mov_b32 s66, s56
	s_mov_b32 s67, s56
	s_mov_b32 s68, s56
	s_mov_b32 s69, s56
	s_mov_b32 s70, s56
	s_mov_b32 s71, s56
	v_add_u32_e32 v177, s6, v48
	v_lshl_add_u32 v176, v138, 2, v174
	v_mov_b32_e32 v178, 0
	s_waitcnt vmcnt(3)
	ds_write_b128 v134, v[2:5]
	v_and_b32_e32 v2, 0x70, v18
	v_bitop3_b32 v1, v0, v1, v2 bitop3:0xde
	v_add_u32_e32 v175, 0, v1
	v_lshlrev_b32_e32 v1, 8, v20
	v_bitop3_b32 v0, v0, v1, v2 bitop3:0xde
	v_add_u32_e32 v180, 0, v0
	s_waitcnt vmcnt(2)
	ds_write_b128 v145, v[6:9]
	s_waitcnt vmcnt(1)
	ds_write_b128 v175, v[10:13] offset:32768
	s_waitcnt vmcnt(0)
	ds_write_b128 v180, v[14:17] offset:32768
	s_waitcnt lgkmcnt(0)
	s_barrier
	ds_read_b128 v[16:19], v181 offset:32768
	ds_read_b128 v[20:23], v181 offset:40960
	s_waitcnt lgkmcnt(1)
	v_mfma_f32_32x32x16_bf16 v[32:47], v[16:19], v[108:111], 0
	ds_read_b128 v[50:53], v182 offset:32768
	ds_read_b128 v[54:57], v182 offset:40960
	v_mov_b64_e32 v[0:1], s[56:57]
	v_mov_b64_e32 v[14:15], s[70:71]
	v_mov_b64_e32 v[2:3], s[58:59]
	v_mov_b64_e32 v[4:5], s[60:61]
	v_mov_b64_e32 v[6:7], s[62:63]
	v_mov_b64_e32 v[8:9], s[64:65]
	s_waitcnt lgkmcnt(2)
	v_mfma_f32_32x32x16_bf16 v[16:31], v[20:23], v[108:111], 0
	v_mov_b64_e32 v[10:11], s[66:67]
	v_mov_b64_e32 v[12:13], s[68:69]
	s_mov_b32 s57, -1
	s_mov_b64 s[58:59], 0
	s_waitcnt lgkmcnt(1)
	v_mfma_f32_32x32x16_bf16 v[32:47], v[50:53], v[104:107], v[32:47]
	s_waitcnt lgkmcnt(0)
	v_mfma_f32_32x32x16_bf16 v[16:31], v[54:57], v[104:107], v[16:31]
	ds_read_b128 v[50:53], v183 offset:32768
	ds_read_b128 v[54:57], v183 offset:40960
	s_waitcnt lgkmcnt(1)
	v_mfma_f32_32x32x16_bf16 v[32:47], v[50:53], v[100:103], v[32:47]
	s_waitcnt lgkmcnt(0)
	v_mfma_f32_32x32x16_bf16 v[16:31], v[54:57], v[100:103], v[16:31]
	ds_read_b128 v[50:53], v184 offset:32768
	ds_read_b128 v[54:57], v184 offset:40960
	s_waitcnt lgkmcnt(1)
	v_mfma_f32_32x32x16_bf16 v[32:47], v[50:53], v[96:99], v[32:47]
	s_waitcnt lgkmcnt(0)
	v_mfma_f32_32x32x16_bf16 v[16:31], v[54:57], v[96:99], v[16:31]
	s_nop 9
	v_max_f32_e32 v49, v33, v33
	v_max_f32_e32 v50, v32, v32
	v_max_f32_e32 v49, v50, v49
	v_max3_f32 v49, v49, v34, v35
	v_max3_f32 v49, v49, v36, v37
	v_max3_f32 v49, v49, v38, v39
	v_max3_f32 v49, v49, v40, v41
	v_max3_f32 v49, v49, v42, v43
	v_max3_f32 v49, v49, v44, v45
	v_max3_f32 v49, v49, v46, v47
	v_max3_f32 v49, v49, v16, v17
	v_max3_f32 v49, v49, v18, v19
	v_max3_f32 v49, v49, v20, v21
	v_max3_f32 v49, v49, v22, v23
	v_max3_f32 v49, v49, v24, v25
	v_max3_f32 v49, v49, v26, v27
	v_max3_f32 v49, v49, v28, v29
	v_max3_f32 v49, v49, v30, v31
	v_mov_b32_e32 v50, v49
	s_nop 1
	v_permlane32_swap_b32_e32 v49, v50
	v_max_f32_e32 v50, v50, v50
	v_max_f32_e32 v49, v49, v49
	v_max_f32_e32 v49, v49, v50
	v_add_f32_e32 v50, 0x7149f2ca, v49
	v_cmp_ge_f32_e32 vcc, s33, v50
	s_cmp_eq_u64 vcc, exec
	s_cselect_b64 vcc, -1, 0
	v_max_f32_e32 v49, 0xf149f2ca, v49
	v_cndmask_b32_e32 v186, v49, v164, vcc
	v_sub_f32_e32 v50, 0xf149f2ca, v49
	v_mul_f32_e32 v49, 0xbe38aa3b, v186
	v_fmamk_f32 v32, v32, 0x3e38aa3b, v49
	v_fmamk_f32 v16, v16, 0x3e38aa3b, v49
	v_exp_f32_e32 v129, v32
	v_fmamk_f32 v32, v33, 0x3e38aa3b, v49
	v_exp_f32_e32 v120, v16
	v_fmamk_f32 v16, v17, 0x3e38aa3b, v49
	v_exp_f32_e32 v131, v32
	v_fmamk_f32 v32, v34, 0x3e38aa3b, v49
	v_exp_f32_e32 v122, v16
	v_fmamk_f32 v16, v18, 0x3e38aa3b, v49
	v_exp_f32_e32 v130, v32
	v_fmamk_f32 v32, v35, 0x3e38aa3b, v49
	v_exp_f32_e32 v121, v16
	v_fmamk_f32 v16, v19, 0x3e38aa3b, v49
	v_exp_f32_e32 v198, v32
	v_fmamk_f32 v32, v36, 0x3e38aa3b, v49
	v_exp_f32_e32 v124, v16
	v_fmamk_f32 v16, v20, 0x3e38aa3b, v49
	v_exp_f32_e32 v197, v32
	v_fmamk_f32 v32, v37, 0x3e38aa3b, v49
	v_exp_f32_e32 v123, v16
	v_fmamk_f32 v16, v21, 0x3e38aa3b, v49
	v_mul_f32_e32 v50, 0x3e38aa3b, v50
	v_exp_f32_e32 v200, v32
	v_fmamk_f32 v32, v38, 0x3e38aa3b, v49
	v_exp_f32_e32 v126, v16
	v_fmamk_f32 v16, v22, 0x3e38aa3b, v49
	v_exp_f32_e32 v50, v50
	v_exp_f32_e32 v199, v32
	v_fmamk_f32 v32, v39, 0x3e38aa3b, v49
	v_exp_f32_e32 v125, v16
	v_fmamk_f32 v16, v23, 0x3e38aa3b, v49
	v_exp_f32_e32 v201, v32
	v_fmamk_f32 v32, v40, 0x3e38aa3b, v49
	v_exp_f32_e32 v127, v16
	v_fmamk_f32 v16, v24, 0x3e38aa3b, v49
	v_exp_f32_e32 v189, v32
	v_fmamk_f32 v32, v41, 0x3e38aa3b, v49
	v_exp_f32_e32 v112, v16
	v_fmamk_f32 v16, v25, 0x3e38aa3b, v49
	v_exp_f32_e32 v192, v32
	v_fmamk_f32 v32, v42, 0x3e38aa3b, v49
	v_exp_f32_e32 v114, v16
	v_fmamk_f32 v16, v26, 0x3e38aa3b, v49
	v_cndmask_b32_e64 v185, v50, 1.0, vcc
	v_exp_f32_e32 v190, v32
	v_fmamk_f32 v32, v43, 0x3e38aa3b, v49
	v_exp_f32_e32 v113, v16
	v_fmamk_f32 v16, v27, 0x3e38aa3b, v49
	v_add_co_u32_e32 v24, vcc, s4, v146
	v_exp_f32_e32 v194, v32
	v_fmamk_f32 v32, v44, 0x3e38aa3b, v49
	v_exp_f32_e32 v116, v16
	v_fmamk_f32 v16, v28, 0x3e38aa3b, v49
	v_addc_co_u32_e32 v25, vcc, 0, v147, vcc
	v_exp_f32_e32 v193, v32
	v_fmamk_f32 v32, v45, 0x3e38aa3b, v49
	v_exp_f32_e32 v115, v16
	v_fmamk_f32 v16, v29, 0x3e38aa3b, v49
	v_add_co_u32_e32 v28, vcc, s4, v148
	v_exp_f32_e32 v196, v32
	v_fmamk_f32 v32, v46, 0x3e38aa3b, v49
	v_exp_f32_e32 v118, v16
	v_fmamk_f32 v16, v30, 0x3e38aa3b, v49
	v_addc_co_u32_e32 v29, vcc, 0, v149, vcc
	v_exp_f32_e32 v191, v32
	v_fmamk_f32 v32, v47, 0x3e38aa3b, v49
	v_exp_f32_e32 v117, v16
	v_fmac_f32_e32 v49, 0x3e38aa3b, v31
	global_load_dwordx4 v[16:19], v[24:25], off offset:1024
	global_load_dwordx4 v[20:23], v[28:29], off offset:1024
	s_nop 0
	global_load_dwordx4 v[24:27], v[24:25], off
	s_nop 0
	global_load_dwordx4 v[28:31], v[28:29], off
	v_exp_f32_e32 v195, v32
	v_exp_f32_e32 v119, v49
	s_waitcnt vmcnt(0)
	s_addk_i32 s6, 0x4000
	s_waitcnt vmcnt(3)
	ds_write_b128 v134, v[16:19] offset:16384
	s_waitcnt vmcnt(2)
	ds_write_b128 v145, v[20:23] offset:16384
	s_waitcnt vmcnt(1)
	ds_write_b128 v175, v[24:27] offset:49152
	s_waitcnt vmcnt(0)
	ds_write_b128 v180, v[28:31] offset:49152
	v_add_u32_e32 v179, s6, v48
	v_mov_b64_e32 v[62:63], v[14:15]
	v_mov_b64_e32 v[46:47], v[14:15]
	v_mov_b64_e32 v[30:31], v[14:15]
	v_cmp_gt_u32_e64 s[4:5], 32, v171
	v_mov_b64_e32 v[60:61], v[12:13]
	v_mov_b64_e32 v[58:59], v[10:11]
	v_mov_b64_e32 v[56:57], v[8:9]
	v_mov_b64_e32 v[54:55], v[6:7]
	v_mov_b64_e32 v[52:53], v[4:5]
	v_mov_b64_e32 v[50:51], v[2:3]
	v_mov_b64_e32 v[48:49], v[0:1]
	v_mov_b64_e32 v[44:45], v[12:13]
	v_mov_b64_e32 v[42:43], v[10:11]
	v_mov_b64_e32 v[40:41], v[8:9]
	v_mov_b64_e32 v[38:39], v[6:7]
	v_mov_b64_e32 v[36:37], v[4:5]
	v_mov_b64_e32 v[34:35], v[2:3]
	v_mov_b64_e32 v[32:33], v[0:1]
	v_mov_b64_e32 v[28:29], v[12:13]
	v_mov_b64_e32 v[26:27], v[10:11]
	v_mov_b64_e32 v[24:25], v[8:9]
	v_mov_b64_e32 v[22:23], v[6:7]
	v_mov_b64_e32 v[20:21], v[4:5]
	v_mov_b64_e32 v[18:19], v[2:3]
	v_mov_b64_e32 v[16:17], v[0:1]
	s_waitcnt lgkmcnt(0)
	s_barrier

.LBB0_219:
	v_cndmask_b32_e64 v186, v128, v186, s[6:7]
	v_mul_f32_e32 v120, 0xbe38aa3b, v186
	v_pk_fma_f32 v[80:81], v[80:81], s[100:101], v[120:121] op_sel_hi:[1,1,0]
	v_pk_fma_f32 v[64:65], v[64:65], s[100:101], v[120:121] op_sel_hi:[1,1,0]
	v_exp_f32_e32 v128, v80
	v_exp_f32_e32 v130, v81
	v_pk_fma_f32 v[82:83], v[82:83], s[100:101], v[120:121] op_sel_hi:[1,1,0]
	v_exp_f32_e32 v119, v64
	v_exp_f32_e32 v122, v65
	v_pk_fma_f32 v[66:67], v[66:67], s[100:101], v[120:121] op_sel_hi:[1,1,0]
	v_exp_f32_e32 v129, v82
	v_exp_f32_e32 v197, v83
	v_pk_fma_f32 v[84:85], v[84:85], s[100:101], v[120:121] op_sel_hi:[1,1,0]
	v_exp_f32_e32 v121, v66
	v_exp_f32_e32 v124, v67
	v_pk_fma_f32 v[68:69], v[68:69], s[100:101], v[120:121] op_sel_hi:[1,1,0]
	v_exp_f32_e32 v131, v84
	v_exp_f32_e32 v199, v85
	v_pk_fma_f32 v[86:87], v[86:87], s[100:101], v[120:121] op_sel_hi:[1,1,0]
	v_exp_f32_e32 v123, v68
	v_exp_f32_e32 v126, v69
	v_pk_fma_f32 v[70:71], v[70:71], s[100:101], v[120:121] op_sel_hi:[1,1,0]
	v_exp_f32_e32 v198, v86
	v_exp_f32_e32 v200, v87
	v_pk_fma_f32 v[88:89], v[88:89], s[100:101], v[120:121] op_sel_hi:[1,1,0]
	v_exp_f32_e32 v125, v70
	v_exp_f32_e32 v127, v71
	v_pk_fma_f32 v[72:73], v[72:73], s[100:101], v[120:121] op_sel_hi:[1,1,0]
	v_exp_f32_e32 v189, v88
	v_exp_f32_e32 v191, v89
	v_pk_fma_f32 v[90:91], v[90:91], s[100:101], v[120:121] op_sel_hi:[1,1,0]
	v_exp_f32_e32 v112, v72
	v_exp_f32_e32 v114, v73
	v_pk_fma_f32 v[74:75], v[74:75], s[100:101], v[120:121] op_sel_hi:[1,1,0]
	v_exp_f32_e32 v190, v90
	v_exp_f32_e32 v193, v91
	v_pk_fma_f32 v[92:93], v[92:93], s[100:101], v[120:121] op_sel_hi:[1,1,0]
	v_exp_f32_e32 v113, v74
	v_exp_f32_e32 v116, v75
	v_pk_fma_f32 v[76:77], v[76:77], s[100:101], v[120:121] op_sel_hi:[1,1,0]
	v_exp_f32_e32 v192, v92
	v_exp_f32_e32 v195, v93
	v_pk_fma_f32 v[94:95], v[94:95], s[100:101], v[120:121] op_sel_hi:[1,1,0]
	v_exp_f32_e32 v115, v76
	v_exp_f32_e32 v118, v77
	v_pk_fma_f32 v[78:79], v[78:79], s[100:101], v[120:121] op_sel_hi:[1,1,0]
	v_exp_f32_e32 v194, v94
	v_exp_f32_e32 v196, v95
	s_nop 0
	v_exp_f32_e32 v117, v78
	v_exp_f32_e32 v120, v79
	s_waitcnt lgkmcnt(0)
	s_barrier
	ds_read_b128 v[64:67], v181 offset:32768
	ds_read_b128 v[68:71], v181 offset:40960
	v_add_f32_e32 v201, 0, v128
	v_add_f32_e32 v201, v130, v201
	v_add_f32_e32 v201, v129, v201
	s_waitcnt lgkmcnt(1)
	v_mfma_f32_32x32x16_bf16 v[80:95], v[64:67], v[108:111], 0
	v_add_f32_e32 v201, v197, v201
	v_add_f32_e32 v201, v131, v201
	ds_read_b128 v[204:207], v182 offset:32768
	ds_read_b128 v[208:211], v182 offset:40960
	v_add_f32_e32 v201, v199, v201
	v_add_f32_e32 v201, v198, v201
	v_add_f32_e32 v201, v200, v201
	v_add_f32_e32 v201, v189, v201
	s_waitcnt lgkmcnt(2)
	v_mfma_f32_32x32x16_bf16 v[64:79], v[68:71], v[108:111], 0
	v_add_f32_e32 v201, v191, v201
	v_add_f32_e32 v201, v190, v201
	v_add_f32_e32 v201, v193, v201
	v_add_f32_e32 v201, v192, v201
	v_add_f32_e32 v201, v195, v201
	v_add_f32_e32 v201, v194, v201
	v_add_f32_e32 v201, v196, v201
	s_waitcnt lgkmcnt(1)
	v_mfma_f32_32x32x16_bf16 v[80:95], v[204:207], v[104:107], v[80:95]
	v_add_f32_e32 v201, v119, v201
	v_add_f32_e32 v201, v122, v201
	v_add_f32_e32 v201, v121, v201
	v_add_f32_e32 v201, v124, v201
	v_add_f32_e32 v201, v123, v201
	v_add_f32_e32 v201, v126, v201
	v_add_f32_e32 v201, v125, v201
	s_waitcnt lgkmcnt(0)
	v_mfma_f32_32x32x16_bf16 v[64:79], v[208:211], v[104:107], v[64:79]
	ds_read_b128 v[204:207], v183 offset:32768
	ds_read_b128 v[208:211], v183 offset:40960
	v_add_f32_e32 v201, v127, v201
	v_add_f32_e32 v201, v112, v201
	v_add_f32_e32 v201, v114, v201
	v_add_f32_e32 v201, v113, v201
	v_add_f32_e32 v201, v116, v201
	v_add_f32_e32 v201, v115, v201
	s_waitcnt lgkmcnt(1)
	v_mfma_f32_32x32x16_bf16 v[80:95], v[204:207], v[100:103], v[80:95]
	v_add_f32_e32 v201, v118, v201
	v_add_f32_e32 v201, v117, v201
	v_add_f32_e32 v203, v120, v201
	s_waitcnt lgkmcnt(0)
	v_mfma_f32_32x32x16_bf16 v[64:79], v[208:211], v[100:103], v[64:79]
	ds_read_b128 v[204:207], v184 offset:32768
	ds_read_b128 v[208:211], v184 offset:40960
	v_cvt_pk_bf16_f32 v128, v128, v130
	v_cvt_pk_bf16_f32 v129, v129, v197
	v_cvt_pk_bf16_f32 v130, v131, v199
	v_cvt_pk_bf16_f32 v131, v198, v200
	v_cvt_pk_bf16_f32 v198, v189, v191
	v_cvt_pk_bf16_f32 v199, v190, v193
	s_waitcnt lgkmcnt(1)
	v_mfma_f32_32x32x16_bf16 v[80:95], v[204:207], v[96:99], v[80:95]
	v_mov_b32_e32 v204, v203
	s_nop 1
	v_permlane32_swap_b32_e32 v203, v204
	v_permlane32_swap_b32_e32 v128, v130
	v_permlane32_swap_b32_e32 v129, v131
	s_waitcnt lgkmcnt(0)
	v_mfma_f32_32x32x16_bf16 v[64:79], v[208:211], v[96:99], v[64:79]
	v_cvt_pk_bf16_f32 v200, v192, v195
	v_cvt_pk_bf16_f32 v201, v194, v196
	v_cvt_pk_bf16_f32 v190, v119, v122
	v_cvt_pk_bf16_f32 v191, v121, v124
	v_cvt_pk_bf16_f32 v192, v123, v126
	v_cvt_pk_bf16_f32 v193, v125, v127
	v_cvt_pk_bf16_f32 v194, v112, v114
	v_cvt_pk_bf16_f32 v195, v113, v116
	v_cvt_pk_bf16_f32 v196, v115, v118
	v_cvt_pk_bf16_f32 v197, v117, v120
	s_nop 0
	v_permlane32_swap_b32_e32 v198, v200
	v_permlane32_swap_b32_e32 v199, v201
	v_permlane32_swap_b32_e32 v190, v192
	v_permlane32_swap_b32_e32 v191, v193
	v_permlane32_swap_b32_e32 v194, v196
	v_permlane32_swap_b32_e32 v195, v197
	v_add_co_u32_e32 v116, vcc, s78, v152
	s_nop 1
	v_addc_co_u32_e32 v117, vcc, 0, v153, vcc
	v_add_co_u32_e32 v120, vcc, s78, v150
	s_nop 1
	v_addc_co_u32_e32 v121, vcc, 0, v151, vcc
	global_load_dwordx4 v[112:115], v[116:117], off offset:1024
	s_nop 0
	global_load_dwordx4 v[116:119], v[116:117], off
	s_nop 0
	global_load_dwordx4 v[124:127], v[120:121], off offset:1024
	s_nop 0
	global_load_dwordx4 v[120:123], v[120:121], off
	ds_read_b64_tr_b16 v[150:151], v179 offset:0
	ds_read_b64_tr_b16 v[152:153], v179 offset:0x800
	ds_read_b64_tr_b16 v[206:207], v179 offset:0x1000
	ds_read_b64_tr_b16 v[208:209], v179 offset:0x1800
	ds_read_b64_tr_b16 v[210:211], v179 offset:0x2000
	ds_read_b64_tr_b16 v[212:213], v179 offset:0x2800
	ds_read_b64_tr_b16 v[214:215], v179 offset:0x3000
	ds_read_b64_tr_b16 v[216:217], v179 offset:0x3800
	s_waitcnt lgkmcnt(0)
	s_nop 0
	v_mfma_f32_32x32x16_bf16 v[0:15], v[128:131], v[150:153], v[0:15]
	ds_read_b64_tr_b16 v[150:151], v179 offset:0x200
	ds_read_b64_tr_b16 v[152:153], v179 offset:0xa00
	v_mfma_f32_32x32x16_bf16 v[0:15], v[198:201], v[206:209], v[0:15]
	ds_read_b64_tr_b16 v[206:207], v179 offset:0x1200
	ds_read_b64_tr_b16 v[208:209], v179 offset:0x1a00
	v_mfma_f32_32x32x16_bf16 v[0:15], v[190:193], v[210:213], v[0:15]
	ds_read_b64_tr_b16 v[210:211], v179 offset:0x2200
	ds_read_b64_tr_b16 v[212:213], v179 offset:0x2a00
	v_mfma_f32_32x32x16_bf16 v[0:15], v[194:197], v[214:217], v[0:15]
	ds_read_b64_tr_b16 v[214:215], v179 offset:0x3200
	ds_read_b64_tr_b16 v[216:217], v179 offset:0x3a00
	s_waitcnt lgkmcnt(0)
	v_mfma_f32_32x32x16_bf16 v[48:63], v[128:131], v[150:153], v[48:63]
	ds_read_b64_tr_b16 v[150:151], v179 offset:0x400
	ds_read_b64_tr_b16 v[152:153], v179 offset:0xc00
	v_mfma_f32_32x32x16_bf16 v[48:63], v[198:201], v[206:209], v[48:63]
	ds_read_b64_tr_b16 v[206:207], v179 offset:0x1400
	ds_read_b64_tr_b16 v[208:209], v179 offset:0x1c00
	v_mfma_f32_32x32x16_bf16 v[48:63], v[190:193], v[210:213], v[48:63]
	ds_read_b64_tr_b16 v[210:211], v179 offset:0x2400
	ds_read_b64_tr_b16 v[212:213], v179 offset:0x2c00
	v_mfma_f32_32x32x16_bf16 v[48:63], v[194:197], v[214:217], v[48:63]
	ds_read_b64_tr_b16 v[214:215], v179 offset:0x3400
	ds_read_b64_tr_b16 v[216:217], v179 offset:0x3c00
	s_waitcnt lgkmcnt(0)
	v_mfma_f32_32x32x16_bf16 v[32:47], v[128:131], v[150:153], v[32:47]
	ds_read_b64_tr_b16 v[150:151], v179 offset:0x600
	ds_read_b64_tr_b16 v[152:153], v179 offset:0xe00
	v_mfma_f32_32x32x16_bf16 v[32:47], v[198:201], v[206:209], v[32:47]
	ds_read_b64_tr_b16 v[206:207], v179 offset:0x1600
	ds_read_b64_tr_b16 v[208:209], v179 offset:0x1e00
	v_mfma_f32_32x32x16_bf16 v[32:47], v[190:193], v[210:213], v[32:47]
	ds_read_b64_tr_b16 v[210:211], v179 offset:0x2600
	ds_read_b64_tr_b16 v[212:213], v179 offset:0x2e00
	v_mfma_f32_32x32x16_bf16 v[32:47], v[194:197], v[214:217], v[32:47]
	ds_read_b64_tr_b16 v[214:215], v179 offset:0x3600
	ds_read_b64_tr_b16 v[216:217], v179 offset:0x3e00
	s_waitcnt lgkmcnt(0)
	v_mfma_f32_32x32x16_bf16 v[16:31], v[128:131], v[150:153], v[16:31]
	v_max_f32_e32 v128, v81, v81
	v_max_f32_e32 v129, v80, v80
	v_max_f32_e32 v128, v129, v128
	v_max3_f32 v128, v128, v82, v83
	v_max3_f32 v128, v128, v84, v85
	v_max3_f32 v128, v128, v86, v87
	v_max3_f32 v128, v128, v88, v89
	v_max3_f32 v128, v128, v90, v91
	v_max3_f32 v128, v128, v92, v93
	v_mfma_f32_32x32x16_bf16 v[16:31], v[198:201], v[206:209], v[16:31]
	v_max3_f32 v128, v128, v94, v95
	v_max3_f32 v128, v128, v64, v65
	v_max3_f32 v128, v128, v66, v67
	v_max3_f32 v128, v128, v68, v69
	v_max3_f32 v128, v128, v70, v71
	v_max3_f32 v128, v128, v72, v73
	v_max3_f32 v128, v128, v74, v75
	v_max3_f32 v128, v128, v76, v77
	v_mfma_f32_32x32x16_bf16 v[16:31], v[190:193], v[210:213], v[16:31]
	v_max3_f32 v128, v128, v78, v79
	v_mov_b32_e32 v129, v128
	s_nop 1
	v_permlane32_swap_b32_e32 v128, v129
	v_max_f32_e32 v129, v129, v129
	v_max_f32_e32 v128, v128, v128
	v_max_f32_e32 v128, v128, v129
	v_sub_f32_e32 v129, v128, v186
	v_cmp_ge_f32_e32 vcc, s33, v129
	v_max_f32_e32 v129, v186, v186
	v_max_f32_e32 v129, v129, v128
	v_mfma_f32_32x32x16_bf16 v[16:31], v[194:197], v[214:217], v[16:31]
	v_sub_f32_e32 v128, v186, v129
	v_mul_f32_e32 v128, 0x3e38aa3b, v128
	v_exp_f32_e32 v128, v128
	s_cmp_eq_u64 vcc, exec
	s_cselect_b64 s[6:7], -1, 0
	s_barrier
	s_waitcnt vmcnt(0)
	v_cndmask_b32_e64 v128, v128, 1.0, s[6:7]
	v_cmp_gt_f32_e32 vcc, 1.0, v128
	s_waitcnt vmcnt(3)
	ds_write_b128 v134, v[112:115] offset:16384
	s_waitcnt vmcnt(1)
	ds_write_b128 v145, v[124:127] offset:16384
	ds_write_b128 v175, v[116:119] offset:49152
	s_waitcnt vmcnt(0)
	ds_write_b128 v180, v[120:123] offset:49152
	s_cbranch_vccz .LBB0_223
	s_and_saveexec_b64 s[60:61], s[4:5]
	ds_write_b32 v176, v128 offset:128
	s_or_b64 exec, exec, s[60:61]
	s_waitcnt lgkmcnt(0)
	v_add_u32_e32 v124, v174, v144
	ds_read_b128 v[112:115], v124 offset:224
	ds_read_b128 v[116:119], v124 offset:192
	ds_read_b128 v[120:123], v124 offset:160
	ds_read_b128 v[124:127], v124 offset:128
	s_waitcnt lgkmcnt(3)
	v_pk_mul_f32 v[12:13], v[12:13], v[112:113]
	s_waitcnt lgkmcnt(2)
	v_pk_mul_f32 v[8:9], v[8:9], v[116:117]
	s_waitcnt lgkmcnt(1)
	v_pk_mul_f32 v[4:5], v[4:5], v[120:121]
	v_pk_mul_f32 v[14:15], v[14:15], v[114:115]
	v_pk_mul_f32 v[10:11], v[10:11], v[118:119]
	v_pk_mul_f32 v[6:7], v[6:7], v[122:123]
	s_waitcnt lgkmcnt(0)
	v_pk_mul_f32 v[2:3], v[2:3], v[126:127]
	v_pk_mul_f32 v[0:1], v[0:1], v[124:125]
	v_pk_mul_f32 v[60:61], v[60:61], v[112:113]
	v_pk_mul_f32 v[56:57], v[56:57], v[116:117]
	v_pk_mul_f32 v[52:53], v[52:53], v[120:121]
	v_pk_mul_f32 v[62:63], v[62:63], v[114:115]
	v_pk_mul_f32 v[58:59], v[58:59], v[118:119]
	v_pk_mul_f32 v[54:55], v[54:55], v[122:123]
	v_pk_mul_f32 v[50:51], v[50:51], v[126:127]
	v_pk_mul_f32 v[48:49], v[48:49], v[124:125]
	v_pk_mul_f32 v[44:45], v[44:45], v[112:113]
	v_pk_mul_f32 v[40:41], v[40:41], v[116:117]
	v_pk_mul_f32 v[36:37], v[36:37], v[120:121]
	v_pk_mul_f32 v[46:47], v[46:47], v[114:115]
	v_pk_mul_f32 v[42:43], v[42:43], v[118:119]
	v_pk_mul_f32 v[38:39], v[38:39], v[122:123]
	v_pk_mul_f32 v[34:35], v[34:35], v[126:127]
	v_pk_mul_f32 v[32:33], v[32:33], v[124:125]
	v_pk_mul_f32 v[28:29], v[28:29], v[112:113]
	v_pk_mul_f32 v[24:25], v[24:25], v[116:117]
	v_pk_mul_f32 v[20:21], v[20:21], v[120:121]
	v_pk_mul_f32 v[30:31], v[30:31], v[114:115]
	v_pk_mul_f32 v[26:27], v[26:27], v[118:119]
	v_pk_mul_f32 v[22:23], v[22:23], v[122:123]
	v_pk_mul_f32 v[18:19], v[18:19], v[126:127]
	v_pk_mul_f32 v[16:17], v[16:17], v[124:125]
.LBB0_223:
	v_cndmask_b32_e64 v186, v129, v186, s[6:7]
	v_mul_f32_e32 v250, 0xbe38aa3b, v186
	v_pk_fma_f32 v[80:81], v[80:81], s[100:101], v[250:251] op_sel_hi:[1,1,0]
	v_pk_fma_f32 v[64:65], v[64:65], s[100:101], v[250:251] op_sel_hi:[1,1,0]
	v_exp_f32_e32 v129, v80
	v_exp_f32_e32 v131, v81
	v_pk_fma_f32 v[82:83], v[82:83], s[100:101], v[250:251] op_sel_hi:[1,1,0]
	v_exp_f32_e32 v120, v64
	v_exp_f32_e32 v122, v65
	v_pk_fma_f32 v[66:67], v[66:67], s[100:101], v[250:251] op_sel_hi:[1,1,0]
	v_exp_f32_e32 v130, v82
	v_exp_f32_e32 v198, v83
	v_pk_fma_f32 v[84:85], v[84:85], s[100:101], v[250:251] op_sel_hi:[1,1,0]
	v_exp_f32_e32 v121, v66
	v_exp_f32_e32 v124, v67
	v_pk_fma_f32 v[68:69], v[68:69], s[100:101], v[250:251] op_sel_hi:[1,1,0]
	v_exp_f32_e32 v197, v84
	v_exp_f32_e32 v200, v85
	v_pk_fma_f32 v[86:87], v[86:87], s[100:101], v[250:251] op_sel_hi:[1,1,0]
	v_exp_f32_e32 v123, v68
	v_exp_f32_e32 v126, v69
	v_pk_fma_f32 v[70:71], v[70:71], s[100:101], v[250:251] op_sel_hi:[1,1,0]
	v_exp_f32_e32 v199, v86
	v_exp_f32_e32 v201, v87
	v_pk_fma_f32 v[88:89], v[88:89], s[100:101], v[250:251] op_sel_hi:[1,1,0]
	v_exp_f32_e32 v125, v70
	v_exp_f32_e32 v127, v71
	v_pk_fma_f32 v[72:73], v[72:73], s[100:101], v[250:251] op_sel_hi:[1,1,0]
	v_exp_f32_e32 v189, v88
	v_exp_f32_e32 v192, v89
	v_pk_fma_f32 v[90:91], v[90:91], s[100:101], v[250:251] op_sel_hi:[1,1,0]
	v_exp_f32_e32 v112, v72
	v_exp_f32_e32 v114, v73
	v_pk_fma_f32 v[74:75], v[74:75], s[100:101], v[250:251] op_sel_hi:[1,1,0]
	v_exp_f32_e32 v190, v90
	v_exp_f32_e32 v194, v91
	v_pk_fma_f32 v[92:93], v[92:93], s[100:101], v[250:251] op_sel_hi:[1,1,0]
	v_exp_f32_e32 v113, v74
	v_exp_f32_e32 v116, v75
	v_pk_fma_f32 v[76:77], v[76:77], s[100:101], v[250:251] op_sel_hi:[1,1,0]
	v_exp_f32_e32 v193, v92
	v_exp_f32_e32 v196, v93
	v_pk_fma_f32 v[94:95], v[94:95], s[100:101], v[250:251] op_sel_hi:[1,1,0]
	v_exp_f32_e32 v115, v76
	v_exp_f32_e32 v118, v77
	v_pk_fma_f32 v[78:79], v[78:79], s[100:101], v[250:251] op_sel_hi:[1,1,0]
	v_exp_f32_e32 v191, v94
	v_exp_f32_e32 v195, v95
	s_nop 0
	v_exp_f32_e32 v117, v78
	v_exp_f32_e32 v119, v79
	v_add_f32_e32 v64, v187, v188
	s_add_u32 s58, s58, 0xd8000
	v_fmac_f32_e32 v64, v185, v178
	v_add_f32_e32 v178, v203, v204
	s_addc_u32 s59, s59, 0
	s_add_i32 s57, s57, 2
	v_fmac_f32_e32 v178, v64, v202
	s_cmpk_gt_u32 s57, 0x7c
	s_waitcnt lgkmcnt(0)
	s_barrier
	s_cbranch_scc1 .LBB0_225
	v_mov_b32_e32 v185, v128
	s_branch .LBB0_215

.LBB0_1052:
	s_and_saveexec_b64 s[6:7], vcc
	s_xor_b64 s[6:7], exec, s[6:7]
	s_cbranch_execz .LBB0_1062
	s_waitcnt lgkmcnt(0)
	s_barrier
	s_setprio 0
	v_mov_b32_e32 v134, v135
	s_waitcnt vmcnt(0)
	v_mov_b32_e32 v20, 0
	v_mov_b32_e32 v21, 0
	v_mov_b32_e32 v22, 0
	v_mov_b32_e32 v23, 0
	v_add_u32_e32 v89, v55, v59
	v_lshl_add_u32 v90, v51, 2, v55
	s_mov_b32 s52, 0
.Lsc_chunk:
	s_and_b32 s54, s52, 1
	s_mul_i32 s55, s54, 0xa400
	s_lshl_b32 s54, s54, 14
	v_add_u32_e32 v17, s55, v89
	v_add_u32_e32 v19, s55, v90
	v_add_u32_e32 v88, s54, v57
	ds_read_b128 v[0:3], v17 offset:4096
	ds_read_b128 v[4:7], v17 offset:12288
	ds_read_b32 v16, v19 offset:20480
	ds_read_b128 v[8:11], v17 offset:0
	ds_read_b128 v[12:15], v17 offset:8192
	s_waitcnt lgkmcnt(4)
	v_pk_mul_f32 v[76:77], v[20:21], v[0:1]
	ds_read_b128 v[24:27], v17 offset:4352
	v_pk_fma_f32 v[76:77], v[22:23], v[2:3], v[76:77]
	ds_read_b128 v[28:31], v17 offset:12544
	v_add_f32_e32 v76, v76, v77
	ds_read_b32 v18, v19 offset:20512
	ds_read_b128 v[32:35], v17 offset:256
	v_add_f32_dpp v76, v76, v76 quad_perm:[1,0,3,2] row_mask:0xf bank_mask:0xf bound_ctrl:1
	ds_read_b128 v[68:71], v17 offset:16384
	ds_read_b128 v[36:39], v17 offset:8448
	v_add_f32_dpp v76, v76, v76 quad_perm:[2,3,0,1] row_mask:0xf bank_mask:0xf bound_ctrl:1
	s_waitcnt lgkmcnt(6)
	v_pk_mul_f32 v[78:79], v[4:5], v[16:17] op_sel_hi:[1,0]
	v_pk_mul_f32 v[80:81], v[6:7], v[16:17] op_sel_hi:[1,0]
	v_add_f32_dpp v76, v76, v76 row_half_mirror row_mask:0xf bank_mask:0xf bound_ctrl:1
	v_pk_fma_f32 v[78:79], v[20:21], v[8:9], v[78:79]
	s_nop 0
	v_add_f32_dpp v76, v76, v76 row_ror:8 row_mask:0xf bank_mask:0xf bound_ctrl:1
	v_pk_fma_f32 v[80:81], v[22:23], v[10:11], v[80:81]
	v_pk_fma_f32 v[20:21], v[12:13], v[76:77], v[78:79] op_sel_hi:[1,0,1] neg_lo:[1,0,0] neg_hi:[1,0,0]
	v_pk_fma_f32 v[22:23], v[14:15], v[76:77], v[80:81] op_sel_hi:[1,0,1] neg_lo:[1,0,0] neg_hi:[1,0,0]
	s_waitcnt lgkmcnt(5)
	v_pk_mul_f32 v[76:77], v[20:21], v[24:25]
	ds_read_b128 v[40:43], v17 offset:4608
	v_pk_fma_f32 v[76:77], v[22:23], v[26:27], v[76:77]
	ds_read_b128 v[44:47], v17 offset:12800
	v_add_f32_e32 v76, v76, v77
	ds_read_b32 v48, v19 offset:20544
	ds_read_b128 v[60:63], v17 offset:512
	v_add_f32_dpp v76, v76, v76 quad_perm:[1,0,3,2] row_mask:0xf bank_mask:0xf bound_ctrl:1
	ds_read_b128 v[72:75], v17 offset:16640
	ds_read_b128 v[64:67], v17 offset:8704
	v_add_f32_dpp v76, v76, v76 quad_perm:[2,3,0,1] row_mask:0xf bank_mask:0xf bound_ctrl:1
	s_waitcnt lgkmcnt(6)
	v_pk_mul_f32 v[78:79], v[28:29], v[18:19] op_sel_hi:[1,0]
	v_pk_mul_f32 v[80:81], v[30:31], v[18:19] op_sel_hi:[1,0]
	v_add_f32_dpp v76, v76, v76 row_half_mirror row_mask:0xf bank_mask:0xf bound_ctrl:1
	v_pk_mul_f32 v[82:83], v[68:69], v[20:21]
	v_pk_fma_f32 v[78:79], v[20:21], v[32:33], v[78:79]
	v_add_f32_dpp v76, v76, v76 row_ror:8 row_mask:0xf bank_mask:0xf bound_ctrl:1
	v_pk_fma_f32 v[82:83], v[70:71], v[22:23], v[82:83]
	v_pk_fma_f32 v[80:81], v[22:23], v[34:35], v[80:81]
	v_pk_fma_f32 v[20:21], v[36:37], v[76:77], v[78:79] op_sel_hi:[1,0,1] neg_lo:[1,0,0] neg_hi:[1,0,0]
	v_pk_fma_f32 v[22:23], v[38:39], v[76:77], v[80:81] op_sel_hi:[1,0,1] neg_lo:[1,0,0] neg_hi:[1,0,0]
	v_add_f32_e32 v82, v82, v83
	ds_write_b32 v88, v82 offset:0
	s_waitcnt lgkmcnt(6)
	v_pk_mul_f32 v[76:77], v[20:21], v[40:41]
	ds_read_b128 v[0:3], v17 offset:4864
	v_pk_fma_f32 v[76:77], v[22:23], v[42:43], v[76:77]
	ds_read_b128 v[4:7], v17 offset:13056
	v_add_f32_e32 v76, v76, v77
	ds_read_b32 v16, v19 offset:20576
	ds_read_b128 v[8:11], v17 offset:768
	v_add_f32_dpp v76, v76, v76 quad_perm:[1,0,3,2] row_mask:0xf bank_mask:0xf bound_ctrl:1
	ds_read_b128 v[84:87], v17 offset:16896
	ds_read_b128 v[12:15], v17 offset:8960
	v_add_f32_dpp v76, v76, v76 quad_perm:[2,3,0,1] row_mask:0xf bank_mask:0xf bound_ctrl:1
	s_waitcnt lgkmcnt(7)
	v_pk_mul_f32 v[78:79], v[44:45], v[48:49] op_sel_hi:[1,0]
	v_pk_mul_f32 v[80:81], v[46:47], v[48:49] op_sel_hi:[1,0]
	v_add_f32_dpp v76, v76, v76 row_half_mirror row_mask:0xf bank_mask:0xf bound_ctrl:1
	v_pk_mul_f32 v[82:83], v[72:73], v[20:21]
	v_pk_fma_f32 v[78:79], v[20:21], v[60:61], v[78:79]
	v_add_f32_dpp v76, v76, v76 row_ror:8 row_mask:0xf bank_mask:0xf bound_ctrl:1
	v_pk_fma_f32 v[82:83], v[74:75], v[22:23], v[82:83]
	v_pk_fma_f32 v[80:81], v[22:23], v[62:63], v[80:81]
	v_pk_fma_f32 v[20:21], v[64:65], v[76:77], v[78:79] op_sel_hi:[1,0,1] neg_lo:[1,0,0] neg_hi:[1,0,0]
	v_pk_fma_f32 v[22:23], v[66:67], v[76:77], v[80:81] op_sel_hi:[1,0,1] neg_lo:[1,0,0] neg_hi:[1,0,0]
	v_add_f32_e32 v82, v82, v83
	ds_write_b32 v88, v82 offset:512
	s_waitcnt lgkmcnt(6)
	v_pk_mul_f32 v[76:77], v[20:21], v[0:1]
	ds_read_b128 v[24:27], v17 offset:5120
	v_pk_fma_f32 v[76:77], v[22:23], v[2:3], v[76:77]
	ds_read_b128 v[28:31], v17 offset:13312
	v_add_f32_e32 v76, v76, v77
	ds_read_b32 v18, v19 offset:20608
	ds_read_b128 v[32:35], v17 offset:1024
	v_add_f32_dpp v76, v76, v76 quad_perm:[1,0,3,2] row_mask:0xf bank_mask:0xf bound_ctrl:1
	ds_read_b128 v[68:71], v17 offset:17152
	ds_read_b128 v[36:39], v17 offset:9216
	v_add_f32_dpp v76, v76, v76 quad_perm:[2,3,0,1] row_mask:0xf bank_mask:0xf bound_ctrl:1
	s_waitcnt lgkmcnt(7)
	v_pk_mul_f32 v[78:79], v[4:5], v[16:17] op_sel_hi:[1,0]
	v_pk_mul_f32 v[80:81], v[6:7], v[16:17] op_sel_hi:[1,0]
	v_add_f32_dpp v76, v76, v76 row_half_mirror row_mask:0xf bank_mask:0xf bound_ctrl:1
	v_pk_mul_f32 v[82:83], v[84:85], v[20:21]
	v_pk_fma_f32 v[78:79], v[20:21], v[8:9], v[78:79]
	v_add_f32_dpp v76, v76, v76 row_ror:8 row_mask:0xf bank_mask:0xf bound_ctrl:1
	v_pk_fma_f32 v[82:83], v[86:87], v[22:23], v[82:83]
	v_pk_fma_f32 v[80:81], v[22:23], v[10:11], v[80:81]
	v_pk_fma_f32 v[20:21], v[12:13], v[76:77], v[78:79] op_sel_hi:[1,0,1] neg_lo:[1,0,0] neg_hi:[1,0,0]
	v_pk_fma_f32 v[22:23], v[14:15], v[76:77], v[80:81] op_sel_hi:[1,0,1] neg_lo:[1,0,0] neg_hi:[1,0,0]
	v_add_f32_e32 v82, v82, v83
	ds_write_b32 v88, v82 offset:1024
	s_waitcnt lgkmcnt(6)
	v_pk_mul_f32 v[76:77], v[20:21], v[24:25]
	ds_read_b128 v[40:43], v17 offset:5376
	v_pk_fma_f32 v[76:77], v[22:23], v[26:27], v[76:77]
	ds_read_b128 v[44:47], v17 offset:13568
	v_add_f32_e32 v76, v76, v77
	ds_read_b32 v48, v19 offset:20640
	ds_read_b128 v[60:63], v17 offset:1280
	v_add_f32_dpp v76, v76, v76 quad_perm:[1,0,3,2] row_mask:0xf bank_mask:0xf bound_ctrl:1
	ds_read_b128 v[72:75], v17 offset:17408
	ds_read_b128 v[64:67], v17 offset:9472
	v_add_f32_dpp v76, v76, v76 quad_perm:[2,3,0,1] row_mask:0xf bank_mask:0xf bound_ctrl:1
	s_waitcnt lgkmcnt(7)
	v_pk_mul_f32 v[78:79], v[28:29], v[18:19] op_sel_hi:[1,0]
	v_pk_mul_f32 v[80:81], v[30:31], v[18:19] op_sel_hi:[1,0]
	v_add_f32_dpp v76, v76, v76 row_half_mirror row_mask:0xf bank_mask:0xf bound_ctrl:1
	v_pk_mul_f32 v[82:83], v[68:69], v[20:21]
	v_pk_fma_f32 v[78:79], v[20:21], v[32:33], v[78:79]
	v_add_f32_dpp v76, v76, v76 row_ror:8 row_mask:0xf bank_mask:0xf bound_ctrl:1
	v_pk_fma_f32 v[82:83], v[70:71], v[22:23], v[82:83]
	v_pk_fma_f32 v[80:81], v[22:23], v[34:35], v[80:81]
	v_pk_fma_f32 v[20:21], v[36:37], v[76:77], v[78:79] op_sel_hi:[1,0,1] neg_lo:[1,0,0] neg_hi:[1,0,0]
	v_pk_fma_f32 v[22:23], v[38:39], v[76:77], v[80:81] op_sel_hi:[1,0,1] neg_lo:[1,0,0] neg_hi:[1,0,0]
	v_add_f32_e32 v82, v82, v83
	ds_write_b32 v88, v82 offset:1536
	s_waitcnt lgkmcnt(6)
	v_pk_mul_f32 v[76:77], v[20:21], v[40:41]
	ds_read_b128 v[0:3], v17 offset:5632
	v_pk_fma_f32 v[76:77], v[22:23], v[42:43], v[76:77]
	ds_read_b128 v[4:7], v17 offset:13824
	v_add_f32_e32 v76, v76, v77
	ds_read_b32 v16, v19 offset:20672
	ds_read_b128 v[8:11], v17 offset:1536
	v_add_f32_dpp v76, v76, v76 quad_perm:[1,0,3,2] row_mask:0xf bank_mask:0xf bound_ctrl:1
	ds_read_b128 v[84:87], v17 offset:17664
	ds_read_b128 v[12:15], v17 offset:9728
	v_add_f32_dpp v76, v76, v76 quad_perm:[2,3,0,1] row_mask:0xf bank_mask:0xf bound_ctrl:1
	s_waitcnt lgkmcnt(7)
	v_pk_mul_f32 v[78:79], v[44:45], v[48:49] op_sel_hi:[1,0]
	v_pk_mul_f32 v[80:81], v[46:47], v[48:49] op_sel_hi:[1,0]
	v_add_f32_dpp v76, v76, v76 row_half_mirror row_mask:0xf bank_mask:0xf bound_ctrl:1
	v_pk_mul_f32 v[82:83], v[72:73], v[20:21]
	v_pk_fma_f32 v[78:79], v[20:21], v[60:61], v[78:79]
	v_add_f32_dpp v76, v76, v76 row_ror:8 row_mask:0xf bank_mask:0xf bound_ctrl:1
	v_pk_fma_f32 v[82:83], v[74:75], v[22:23], v[82:83]
	v_pk_fma_f32 v[80:81], v[22:23], v[62:63], v[80:81]
	v_pk_fma_f32 v[20:21], v[64:65], v[76:77], v[78:79] op_sel_hi:[1,0,1] neg_lo:[1,0,0] neg_hi:[1,0,0]
	v_pk_fma_f32 v[22:23], v[66:67], v[76:77], v[80:81] op_sel_hi:[1,0,1] neg_lo:[1,0,0] neg_hi:[1,0,0]
	v_add_f32_e32 v82, v82, v83
	ds_write_b32 v88, v82 offset:2048
	s_waitcnt lgkmcnt(6)
	v_pk_mul_f32 v[76:77], v[20:21], v[0:1]
	ds_read_b128 v[24:27], v17 offset:5888
	v_pk_fma_f32 v[76:77], v[22:23], v[2:3], v[76:77]
	ds_read_b128 v[28:31], v17 offset:14080
	v_add_f32_e32 v76, v76, v77
	ds_read_b32 v18, v19 offset:20704
	ds_read_b128 v[32:35], v17 offset:1792
	v_add_f32_dpp v76, v76, v76 quad_perm:[1,0,3,2] row_mask:0xf bank_mask:0xf bound_ctrl:1
	ds_read_b128 v[68:71], v17 offset:17920
	ds_read_b128 v[36:39], v17 offset:9984
	v_add_f32_dpp v76, v76, v76 quad_perm:[2,3,0,1] row_mask:0xf bank_mask:0xf bound_ctrl:1
	s_waitcnt lgkmcnt(7)
	v_pk_mul_f32 v[78:79], v[4:5], v[16:17] op_sel_hi:[1,0]
	v_pk_mul_f32 v[80:81], v[6:7], v[16:17] op_sel_hi:[1,0]
	v_add_f32_dpp v76, v76, v76 row_half_mirror row_mask:0xf bank_mask:0xf bound_ctrl:1
	v_pk_mul_f32 v[82:83], v[84:85], v[20:21]
	v_pk_fma_f32 v[78:79], v[20:21], v[8:9], v[78:79]
	v_add_f32_dpp v76, v76, v76 row_ror:8 row_mask:0xf bank_mask:0xf bound_ctrl:1
	v_pk_fma_f32 v[82:83], v[86:87], v[22:23], v[82:83]
	v_pk_fma_f32 v[80:81], v[22:23], v[10:11], v[80:81]
	v_pk_fma_f32 v[20:21], v[12:13], v[76:77], v[78:79] op_sel_hi:[1,0,1] neg_lo:[1,0,0] neg_hi:[1,0,0]
	v_pk_fma_f32 v[22:23], v[14:15], v[76:77], v[80:81] op_sel_hi:[1,0,1] neg_lo:[1,0,0] neg_hi:[1,0,0]
	v_add_f32_e32 v82, v82, v83
	ds_write_b32 v88, v82 offset:2560
	s_waitcnt lgkmcnt(6)
	v_pk_mul_f32 v[76:77], v[20:21], v[24:25]
	ds_read_b128 v[40:43], v17 offset:6144
	v_pk_fma_f32 v[76:77], v[22:23], v[26:27], v[76:77]
	ds_read_b128 v[44:47], v17 offset:14336
	v_add_f32_e32 v76, v76, v77
	ds_read_b32 v48, v19 offset:20736
	ds_read_b128 v[60:63], v17 offset:2048
	v_add_f32_dpp v76, v76, v76 quad_perm:[1,0,3,2] row_mask:0xf bank_mask:0xf bound_ctrl:1
	ds_read_b128 v[72:75], v17 offset:18176
	ds_read_b128 v[64:67], v17 offset:10240
	v_add_f32_dpp v76, v76, v76 quad_perm:[2,3,0,1] row_mask:0xf bank_mask:0xf bound_ctrl:1
	s_waitcnt lgkmcnt(7)
	v_pk_mul_f32 v[78:79], v[28:29], v[18:19] op_sel_hi:[1,0]
	v_pk_mul_f32 v[80:81], v[30:31], v[18:19] op_sel_hi:[1,0]
	v_add_f32_dpp v76, v76, v76 row_half_mirror row_mask:0xf bank_mask:0xf bound_ctrl:1
	v_pk_mul_f32 v[82:83], v[68:69], v[20:21]
	v_pk_fma_f32 v[78:79], v[20:21], v[32:33], v[78:79]
	v_add_f32_dpp v76, v76, v76 row_ror:8 row_mask:0xf bank_mask:0xf bound_ctrl:1
	v_pk_fma_f32 v[82:83], v[70:71], v[22:23], v[82:83]
	v_pk_fma_f32 v[80:81], v[22:23], v[34:35], v[80:81]
	v_pk_fma_f32 v[20:21], v[36:37], v[76:77], v[78:79] op_sel_hi:[1,0,1] neg_lo:[1,0,0] neg_hi:[1,0,0]
	v_pk_fma_f32 v[22:23], v[38:39], v[76:77], v[80:81] op_sel_hi:[1,0,1] neg_lo:[1,0,0] neg_hi:[1,0,0]
	v_add_f32_e32 v82, v82, v83
	ds_write_b32 v88, v82 offset:3072
	s_waitcnt lgkmcnt(6)
	v_pk_mul_f32 v[76:77], v[20:21], v[40:41]
	ds_read_b128 v[0:3], v17 offset:6400
	v_pk_fma_f32 v[76:77], v[22:23], v[42:43], v[76:77]
	ds_read_b128 v[4:7], v17 offset:14592
	v_add_f32_e32 v76, v76, v77
	ds_read_b32 v16, v19 offset:20768
	ds_read_b128 v[8:11], v17 offset:2304
	v_add_f32_dpp v76, v76, v76 quad_perm:[1,0,3,2] row_mask:0xf bank_mask:0xf bound_ctrl:1
	ds_read_b128 v[84:87], v17 offset:18432
	ds_read_b128 v[12:15], v17 offset:10496
	v_add_f32_dpp v76, v76, v76 quad_perm:[2,3,0,1] row_mask:0xf bank_mask:0xf bound_ctrl:1
	s_waitcnt lgkmcnt(7)
	v_pk_mul_f32 v[78:79], v[44:45], v[48:49] op_sel_hi:[1,0]
	v_pk_mul_f32 v[80:81], v[46:47], v[48:49] op_sel_hi:[1,0]
	v_add_f32_dpp v76, v76, v76 row_half_mirror row_mask:0xf bank_mask:0xf bound_ctrl:1
	v_pk_mul_f32 v[82:83], v[72:73], v[20:21]
	v_pk_fma_f32 v[78:79], v[20:21], v[60:61], v[78:79]
	v_add_f32_dpp v76, v76, v76 row_ror:8 row_mask:0xf bank_mask:0xf bound_ctrl:1
	v_pk_fma_f32 v[82:83], v[74:75], v[22:23], v[82:83]
	v_pk_fma_f32 v[80:81], v[22:23], v[62:63], v[80:81]
	v_pk_fma_f32 v[20:21], v[64:65], v[76:77], v[78:79] op_sel_hi:[1,0,1] neg_lo:[1,0,0] neg_hi:[1,0,0]
	v_pk_fma_f32 v[22:23], v[66:67], v[76:77], v[80:81] op_sel_hi:[1,0,1] neg_lo:[1,0,0] neg_hi:[1,0,0]
	v_add_f32_e32 v82, v82, v83
	ds_write_b32 v88, v82 offset:3584
	s_waitcnt lgkmcnt(6)
	v_pk_mul_f32 v[76:77], v[20:21], v[0:1]
	ds_read_b128 v[24:27], v17 offset:6656
	v_pk_fma_f32 v[76:77], v[22:23], v[2:3], v[76:77]
	ds_read_b128 v[28:31], v17 offset:14848
	v_add_f32_e32 v76, v76, v77
	ds_read_b32 v18, v19 offset:20800
	ds_read_b128 v[32:35], v17 offset:2560
	v_add_f32_dpp v76, v76, v76 quad_perm:[1,0,3,2] row_mask:0xf bank_mask:0xf bound_ctrl:1
	ds_read_b128 v[68:71], v17 offset:18688
	ds_read_b128 v[36:39], v17 offset:10752
	v_add_f32_dpp v76, v76, v76 quad_perm:[2,3,0,1] row_mask:0xf bank_mask:0xf bound_ctrl:1
	s_waitcnt lgkmcnt(7)
	v_pk_mul_f32 v[78:79], v[4:5], v[16:17] op_sel_hi:[1,0]
	v_pk_mul_f32 v[80:81], v[6:7], v[16:17] op_sel_hi:[1,0]
	v_add_f32_dpp v76, v76, v76 row_half_mirror row_mask:0xf bank_mask:0xf bound_ctrl:1
	v_pk_mul_f32 v[82:83], v[84:85], v[20:21]
	v_pk_fma_f32 v[78:79], v[20:21], v[8:9], v[78:79]
	v_add_f32_dpp v76, v76, v76 row_ror:8 row_mask:0xf bank_mask:0xf bound_ctrl:1
	v_pk_fma_f32 v[82:83], v[86:87], v[22:23], v[82:83]
	v_pk_fma_f32 v[80:81], v[22:23], v[10:11], v[80:81]
	v_pk_fma_f32 v[20:21], v[12:13], v[76:77], v[78:79] op_sel_hi:[1,0,1] neg_lo:[1,0,0] neg_hi:[1,0,0]
	v_pk_fma_f32 v[22:23], v[14:15], v[76:77], v[80:81] op_sel_hi:[1,0,1] neg_lo:[1,0,0] neg_hi:[1,0,0]
	v_add_f32_e32 v82, v82, v83
	ds_write_b32 v88, v82 offset:4096
	s_waitcnt lgkmcnt(6)
	v_pk_mul_f32 v[76:77], v[20:21], v[24:25]
	ds_read_b128 v[40:43], v17 offset:6912
	v_pk_fma_f32 v[76:77], v[22:23], v[26:27], v[76:77]
	ds_read_b128 v[44:47], v17 offset:15104
	v_add_f32_e32 v76, v76, v77
	ds_read_b32 v48, v19 offset:20832
	ds_read_b128 v[60:63], v17 offset:2816
	v_add_f32_dpp v76, v76, v76 quad_perm:[1,0,3,2] row_mask:0xf bank_mask:0xf bound_ctrl:1
	ds_read_b128 v[72:75], v17 offset:18944
	ds_read_b128 v[64:67], v17 offset:11008
	v_add_f32_dpp v76, v76, v76 quad_perm:[2,3,0,1] row_mask:0xf bank_mask:0xf bound_ctrl:1
	s_waitcnt lgkmcnt(7)
	v_pk_mul_f32 v[78:79], v[28:29], v[18:19] op_sel_hi:[1,0]
	v_pk_mul_f32 v[80:81], v[30:31], v[18:19] op_sel_hi:[1,0]
	v_add_f32_dpp v76, v76, v76 row_half_mirror row_mask:0xf bank_mask:0xf bound_ctrl:1
	v_pk_mul_f32 v[82:83], v[68:69], v[20:21]
	v_pk_fma_f32 v[78:79], v[20:21], v[32:33], v[78:79]
	v_add_f32_dpp v76, v76, v76 row_ror:8 row_mask:0xf bank_mask:0xf bound_ctrl:1
	v_pk_fma_f32 v[82:83], v[70:71], v[22:23], v[82:83]
	v_pk_fma_f32 v[80:81], v[22:23], v[34:35], v[80:81]
	v_pk_fma_f32 v[20:21], v[36:37], v[76:77], v[78:79] op_sel_hi:[1,0,1] neg_lo:[1,0,0] neg_hi:[1,0,0]
	v_pk_fma_f32 v[22:23], v[38:39], v[76:77], v[80:81] op_sel_hi:[1,0,1] neg_lo:[1,0,0] neg_hi:[1,0,0]
	v_add_f32_e32 v82, v82, v83
	ds_write_b32 v88, v82 offset:4608
	s_waitcnt lgkmcnt(6)
	v_pk_mul_f32 v[76:77], v[20:21], v[40:41]
	ds_read_b128 v[0:3], v17 offset:7168
	v_pk_fma_f32 v[76:77], v[22:23], v[42:43], v[76:77]
	ds_read_b128 v[4:7], v17 offset:15360
	v_add_f32_e32 v76, v76, v77
	ds_read_b32 v16, v19 offset:20864
	ds_read_b128 v[8:11], v17 offset:3072
	v_add_f32_dpp v76, v76, v76 quad_perm:[1,0,3,2] row_mask:0xf bank_mask:0xf bound_ctrl:1
	ds_read_b128 v[84:87], v17 offset:19200
	ds_read_b128 v[12:15], v17 offset:11264
	v_add_f32_dpp v76, v76, v76 quad_perm:[2,3,0,1] row_mask:0xf bank_mask:0xf bound_ctrl:1
	s_waitcnt lgkmcnt(7)
	v_pk_mul_f32 v[78:79], v[44:45], v[48:49] op_sel_hi:[1,0]
	v_pk_mul_f32 v[80:81], v[46:47], v[48:49] op_sel_hi:[1,0]
	v_add_f32_dpp v76, v76, v76 row_half_mirror row_mask:0xf bank_mask:0xf bound_ctrl:1
	v_pk_mul_f32 v[82:83], v[72:73], v[20:21]
	v_pk_fma_f32 v[78:79], v[20:21], v[60:61], v[78:79]
	v_add_f32_dpp v76, v76, v76 row_ror:8 row_mask:0xf bank_mask:0xf bound_ctrl:1
	v_pk_fma_f32 v[82:83], v[74:75], v[22:23], v[82:83]
	v_pk_fma_f32 v[80:81], v[22:23], v[62:63], v[80:81]
	v_pk_fma_f32 v[20:21], v[64:65], v[76:77], v[78:79] op_sel_hi:[1,0,1] neg_lo:[1,0,0] neg_hi:[1,0,0]
	v_pk_fma_f32 v[22:23], v[66:67], v[76:77], v[80:81] op_sel_hi:[1,0,1] neg_lo:[1,0,0] neg_hi:[1,0,0]
	v_add_f32_e32 v82, v82, v83
	ds_write_b32 v88, v82 offset:5120
	s_waitcnt lgkmcnt(6)
	v_pk_mul_f32 v[76:77], v[20:21], v[0:1]
	ds_read_b128 v[24:27], v17 offset:7424
	v_pk_fma_f32 v[76:77], v[22:23], v[2:3], v[76:77]
	ds_read_b128 v[28:31], v17 offset:15616
	v_add_f32_e32 v76, v76, v77
	ds_read_b32 v18, v19 offset:20896
	ds_read_b128 v[32:35], v17 offset:3328
	v_add_f32_dpp v76, v76, v76 quad_perm:[1,0,3,2] row_mask:0xf bank_mask:0xf bound_ctrl:1
	ds_read_b128 v[68:71], v17 offset:19456
	ds_read_b128 v[36:39], v17 offset:11520
	v_add_f32_dpp v76, v76, v76 quad_perm:[2,3,0,1] row_mask:0xf bank_mask:0xf bound_ctrl:1
	s_waitcnt lgkmcnt(7)
	v_pk_mul_f32 v[78:79], v[4:5], v[16:17] op_sel_hi:[1,0]
	v_pk_mul_f32 v[80:81], v[6:7], v[16:17] op_sel_hi:[1,0]
	v_add_f32_dpp v76, v76, v76 row_half_mirror row_mask:0xf bank_mask:0xf bound_ctrl:1
	v_pk_mul_f32 v[82:83], v[84:85], v[20:21]
	v_pk_fma_f32 v[78:79], v[20:21], v[8:9], v[78:79]
	v_add_f32_dpp v76, v76, v76 row_ror:8 row_mask:0xf bank_mask:0xf bound_ctrl:1
	v_pk_fma_f32 v[82:83], v[86:87], v[22:23], v[82:83]
	v_pk_fma_f32 v[80:81], v[22:23], v[10:11], v[80:81]
	v_pk_fma_f32 v[20:21], v[12:13], v[76:77], v[78:79] op_sel_hi:[1,0,1] neg_lo:[1,0,0] neg_hi:[1,0,0]
	v_pk_fma_f32 v[22:23], v[14:15], v[76:77], v[80:81] op_sel_hi:[1,0,1] neg_lo:[1,0,0] neg_hi:[1,0,0]
	v_add_f32_e32 v82, v82, v83
	ds_write_b32 v88, v82 offset:5632
	s_waitcnt lgkmcnt(6)
	v_pk_mul_f32 v[76:77], v[20:21], v[24:25]
	ds_read_b128 v[40:43], v17 offset:7680
	v_pk_fma_f32 v[76:77], v[22:23], v[26:27], v[76:77]
	ds_read_b128 v[44:47], v17 offset:15872
	v_add_f32_e32 v76, v76, v77
	ds_read_b32 v48, v19 offset:20928
	ds_read_b128 v[60:63], v17 offset:3584
	v_add_f32_dpp v76, v76, v76 quad_perm:[1,0,3,2] row_mask:0xf bank_mask:0xf bound_ctrl:1
	ds_read_b128 v[72:75], v17 offset:19712
	ds_read_b128 v[64:67], v17 offset:11776
	v_add_f32_dpp v76, v76, v76 quad_perm:[2,3,0,1] row_mask:0xf bank_mask:0xf bound_ctrl:1
	s_waitcnt lgkmcnt(7)
	v_pk_mul_f32 v[78:79], v[28:29], v[18:19] op_sel_hi:[1,0]
	v_pk_mul_f32 v[80:81], v[30:31], v[18:19] op_sel_hi:[1,0]
	v_add_f32_dpp v76, v76, v76 row_half_mirror row_mask:0xf bank_mask:0xf bound_ctrl:1
	v_pk_mul_f32 v[82:83], v[68:69], v[20:21]
	v_pk_fma_f32 v[78:79], v[20:21], v[32:33], v[78:79]
	v_add_f32_dpp v76, v76, v76 row_ror:8 row_mask:0xf bank_mask:0xf bound_ctrl:1
	v_pk_fma_f32 v[82:83], v[70:71], v[22:23], v[82:83]
	v_pk_fma_f32 v[80:81], v[22:23], v[34:35], v[80:81]
	v_pk_fma_f32 v[20:21], v[36:37], v[76:77], v[78:79] op_sel_hi:[1,0,1] neg_lo:[1,0,0] neg_hi:[1,0,0]
	v_pk_fma_f32 v[22:23], v[38:39], v[76:77], v[80:81] op_sel_hi:[1,0,1] neg_lo:[1,0,0] neg_hi:[1,0,0]
	v_add_f32_e32 v82, v82, v83
	ds_write_b32 v88, v82 offset:6144
	s_waitcnt lgkmcnt(6)
	v_pk_mul_f32 v[76:77], v[20:21], v[40:41]
	ds_read_b128 v[0:3], v17 offset:7936
	v_pk_fma_f32 v[76:77], v[22:23], v[42:43], v[76:77]
	ds_read_b128 v[4:7], v17 offset:16128
	v_add_f32_e32 v76, v76, v77
	ds_read_b32 v16, v19 offset:20960
	ds_read_b128 v[8:11], v17 offset:3840
	v_add_f32_dpp v76, v76, v76 quad_perm:[1,0,3,2] row_mask:0xf bank_mask:0xf bound_ctrl:1
	ds_read_b128 v[84:87], v17 offset:19968
	ds_read_b128 v[12:15], v17 offset:12032
	v_add_f32_dpp v76, v76, v76 quad_perm:[2,3,0,1] row_mask:0xf bank_mask:0xf bound_ctrl:1
	s_waitcnt lgkmcnt(7)
	v_pk_mul_f32 v[78:79], v[44:45], v[48:49] op_sel_hi:[1,0]
	v_pk_mul_f32 v[80:81], v[46:47], v[48:49] op_sel_hi:[1,0]
	v_add_f32_dpp v76, v76, v76 row_half_mirror row_mask:0xf bank_mask:0xf bound_ctrl:1
	v_pk_mul_f32 v[82:83], v[72:73], v[20:21]
	v_pk_fma_f32 v[78:79], v[20:21], v[60:61], v[78:79]
	v_add_f32_dpp v76, v76, v76 row_ror:8 row_mask:0xf bank_mask:0xf bound_ctrl:1
	v_pk_fma_f32 v[82:83], v[74:75], v[22:23], v[82:83]
	v_pk_fma_f32 v[80:81], v[22:23], v[62:63], v[80:81]
	v_pk_fma_f32 v[20:21], v[64:65], v[76:77], v[78:79] op_sel_hi:[1,0,1] neg_lo:[1,0,0] neg_hi:[1,0,0]
	v_pk_fma_f32 v[22:23], v[66:67], v[76:77], v[80:81] op_sel_hi:[1,0,1] neg_lo:[1,0,0] neg_hi:[1,0,0]
	v_add_f32_e32 v82, v82, v83
	ds_write_b32 v88, v82 offset:6656
	s_waitcnt lgkmcnt(6)
	v_pk_mul_f32 v[76:77], v[20:21], v[0:1]
	s_nop 0
	v_pk_fma_f32 v[76:77], v[22:23], v[2:3], v[76:77]
	s_nop 0
	v_add_f32_e32 v76, v76, v77
	s_nop 1
	v_add_f32_dpp v76, v76, v76 quad_perm:[1,0,3,2] row_mask:0xf bank_mask:0xf bound_ctrl:1
	ds_read_b128 v[68:71], v17 offset:20224
	s_nop 0
	v_add_f32_dpp v76, v76, v76 quad_perm:[2,3,0,1] row_mask:0xf bank_mask:0xf bound_ctrl:1
	s_waitcnt lgkmcnt(2)
	v_pk_mul_f32 v[78:79], v[4:5], v[16:17] op_sel_hi:[1,0]
	v_pk_mul_f32 v[80:81], v[6:7], v[16:17] op_sel_hi:[1,0]
	v_add_f32_dpp v76, v76, v76 row_half_mirror row_mask:0xf bank_mask:0xf bound_ctrl:1
	v_pk_mul_f32 v[82:83], v[84:85], v[20:21]
	v_pk_fma_f32 v[78:79], v[20:21], v[8:9], v[78:79]
	v_add_f32_dpp v76, v76, v76 row_ror:8 row_mask:0xf bank_mask:0xf bound_ctrl:1
	v_pk_fma_f32 v[82:83], v[86:87], v[22:23], v[82:83]
	v_pk_fma_f32 v[80:81], v[22:23], v[10:11], v[80:81]
	v_pk_fma_f32 v[20:21], v[12:13], v[76:77], v[78:79] op_sel_hi:[1,0,1] neg_lo:[1,0,0] neg_hi:[1,0,0]
	v_pk_fma_f32 v[22:23], v[14:15], v[76:77], v[80:81] op_sel_hi:[1,0,1] neg_lo:[1,0,0] neg_hi:[1,0,0]
	v_add_f32_e32 v82, v82, v83
	ds_write_b32 v88, v82 offset:7168
	s_waitcnt lgkmcnt(1)
	v_pk_mul_f32 v[82:83], v[68:69], v[20:21]
	s_nop 0
	v_pk_fma_f32 v[82:83], v[70:71], v[22:23], v[82:83]
	s_nop 0
	v_add_f32_e32 v82, v82, v83
	ds_write_b32 v88, v82 offset:7680
	s_waitcnt lgkmcnt(0)
	s_barrier
	s_add_i32 s52, s52, 1
	s_cmpk_eq_i32 s52, 0x200
	s_cbranch_scc0 .Lsc_chunk

.LBB0_1124:
	v_and_b32_e32 v254, 1, v149
	v_mul_u32_u24_e32 v254, 24, v254
	v_mov_b32_e32 v255, 0
	v_or_b32_e32 v128, s6, v142
	v_add_u32_e32 v128, v128, v134
	v_or_b32_e32 v130, s7, v143
	v_mov_b64_e32 v[138:139], v[132:133]
	v_ashrrev_i32_e32 v129, 31, v128
	v_ashrrev_i32_e32 v131, 31, v130
	v_lshlrev_b64 v[140:141], 13, v[128:129]
	v_lshl_add_u64 v[138:139], v[138:139], 0, v[140:141]
	v_lshlrev_b64 v[130:131], 1, v[130:131]
	v_max_f32_e32 v124, v124, v124
	v_max_f32_e32 v125, v125, v125
	v_max_f32_e32 v126, v126, v126
	v_lshl_add_u64 v[138:139], v[138:139], 0, v[130:131]
	v_lshlrev_b32_e32 v134, 3, v149
	v_max_f32_e32 v124, 0, v124
	v_max_f32_e32 v125, 0, v125
	v_max_f32_e32 v126, 0, v126
	v_max_f32_e32 v127, v127, v127
	v_lshl_add_u64 v[138:139], v[138:139], 0, v[134:135]
	v_max_f32_e32 v127, 0, v127
	v_mul_f32_e32 v124, v124, v124
	v_mul_f32_e32 v125, v125, v125
	v_mul_f32_e32 v126, v126, v126
	v_max_f32_e32 v120, v120, v120
	v_max_f32_e32 v121, v121, v121
	v_max_f32_e32 v116, v116, v116
	v_max_f32_e32 v117, v117, v117
	v_max_f32_e32 v112, v112, v112
	v_max_f32_e32 v113, v113, v113
	v_max_f32_e32 v108, v108, v108
	v_max_f32_e32 v109, v109, v109
	v_max_f32_e32 v104, v104, v104
	v_max_f32_e32 v105, v105, v105
	v_max_f32_e32 v100, v100, v100
	v_max_f32_e32 v101, v101, v101
	v_max_f32_e32 v96, v96, v96
	v_mul_f32_e32 v127, v127, v127
	v_cvt_pk_bf16_f32 v124, v124, v125
	v_cvt_pk_bf16_f32 v125, v126, v127
	v_max_f32_e32 v120, 0, v120
	v_max_f32_e32 v121, 0, v121
	v_max_f32_e32 v122, v122, v122
	v_max_f32_e32 v123, v123, v123
	v_max_f32_e32 v116, 0, v116
	v_max_f32_e32 v117, 0, v117
	v_max_f32_e32 v118, v118, v118
	v_max_f32_e32 v119, v119, v119
	v_max_f32_e32 v112, 0, v112
	v_max_f32_e32 v113, 0, v113
	v_max_f32_e32 v114, v114, v114
	v_max_f32_e32 v115, v115, v115
	v_max_f32_e32 v108, 0, v108
	v_max_f32_e32 v109, 0, v109
	v_max_f32_e32 v110, v110, v110
	v_max_f32_e32 v111, v111, v111
	v_max_f32_e32 v104, 0, v104
	v_max_f32_e32 v105, 0, v105
	v_max_f32_e32 v106, v106, v106
	v_max_f32_e32 v107, v107, v107
	v_max_f32_e32 v100, 0, v100
	v_max_f32_e32 v101, 0, v101
	v_max_f32_e32 v102, v102, v102
	v_max_f32_e32 v103, v103, v103
	v_max_f32_e32 v96, 0, v96
	v_max_f32_e32 v97, v97, v97
	v_lshl_add_u64 v[140:141], v[138:139], 0, s[22:23]
	v_lshl_add_u64 v[140:141], v[140:141], 0, v[254:255]
	v_max_f32_e32 v122, 0, v122
	v_max_f32_e32 v123, 0, v123
	v_mul_f32_e32 v120, v120, v120
	v_mul_f32_e32 v121, v121, v121
	v_max_f32_e32 v118, 0, v118
	v_max_f32_e32 v119, 0, v119
	v_mul_f32_e32 v116, v116, v116
	v_mul_f32_e32 v117, v117, v117
	v_max_f32_e32 v114, 0, v114
	v_max_f32_e32 v115, 0, v115
	v_mul_f32_e32 v112, v112, v112
	v_mul_f32_e32 v113, v113, v113
	v_max_f32_e32 v110, 0, v110
	v_max_f32_e32 v111, 0, v111
	v_mul_f32_e32 v108, v108, v108
	v_mul_f32_e32 v109, v109, v109
	v_max_f32_e32 v106, 0, v106
	v_max_f32_e32 v107, 0, v107
	v_mul_f32_e32 v104, v104, v104
	v_mul_f32_e32 v105, v105, v105
	v_max_f32_e32 v102, 0, v102
	v_max_f32_e32 v103, 0, v103
	v_mul_f32_e32 v100, v100, v100
	v_mul_f32_e32 v101, v101, v101
	v_max_f32_e32 v97, 0, v97
	v_max_f32_e32 v98, v98, v98
	v_max_f32_e32 v99, v99, v99
	v_mul_f32_e32 v96, v96, v96
	v_mul_f32_e32 v122, v122, v122
	v_mul_f32_e32 v123, v123, v123
	v_cvt_pk_bf16_f32 v126, v120, v121
	v_cvt_pk_bf16_f32 v127, v122, v123
	s_nop 1
	v_permlane16_swap_b32_e32 v124, v126
	v_permlane16_swap_b32_e32 v125, v127
	global_store_dwordx4 v[140:141], v[124:127], off
	s_nop 1
	v_mul_f32_e32 v118, v118, v118
	v_mul_f32_e32 v119, v119, v119
	v_cvt_pk_bf16_f32 v116, v116, v117
	v_cvt_pk_bf16_f32 v117, v118, v119
	v_mul_f32_e32 v114, v114, v114
	v_mul_f32_e32 v115, v115, v115
	v_cvt_pk_bf16_f32 v118, v112, v113
	v_cvt_pk_bf16_f32 v119, v114, v115
	s_nop 1
	v_permlane16_swap_b32_e32 v116, v118
	v_permlane16_swap_b32_e32 v117, v119
	global_store_dwordx4 v[140:141], v[116:119], off offset:64
	s_nop 1
	v_mul_f32_e32 v110, v110, v110
	v_mul_f32_e32 v111, v111, v111
	v_cvt_pk_bf16_f32 v108, v108, v109
	v_cvt_pk_bf16_f32 v109, v110, v111
	v_mul_f32_e32 v106, v106, v106
	v_mul_f32_e32 v107, v107, v107
	v_cvt_pk_bf16_f32 v110, v104, v105
	v_cvt_pk_bf16_f32 v111, v106, v107
	s_nop 1
	v_permlane16_swap_b32_e32 v108, v110
	v_permlane16_swap_b32_e32 v109, v111
	global_store_dwordx4 v[140:141], v[108:111], off offset:128
	s_nop 1
	v_mul_f32_e32 v102, v102, v102
	v_mul_f32_e32 v103, v103, v103
	v_cvt_pk_bf16_f32 v100, v100, v101
	v_cvt_pk_bf16_f32 v101, v102, v103
	v_max_f32_e32 v98, 0, v98
	v_max_f32_e32 v99, 0, v99
	v_mul_f32_e32 v97, v97, v97
	v_cvt_pk_bf16_f32 v102, v96, v97
	v_mul_f32_e32 v98, v98, v98
	v_mul_f32_e32 v99, v99, v99
	v_cvt_pk_bf16_f32 v103, v98, v99
	s_nop 1
	v_permlane16_swap_b32_e32 v100, v102
	v_permlane16_swap_b32_e32 v101, v103
	global_store_dwordx4 v[140:141], v[100:103], off offset:192
	s_nop 1
	v_or_b32_e32 v96, 16, v128
	v_ashrrev_i32_e32 v97, 31, v96
	v_mov_b64_e32 v[98:99], v[132:133]
	v_lshlrev_b64 v[96:97], 13, v[96:97]
	v_max_f32_e32 v92, v92, v92
	v_lshl_add_u64 v[96:97], v[98:99], 0, v[96:97]
	v_max_f32_e32 v93, v93, v93
	v_max_f32_e32 v94, v94, v94
	v_lshl_add_u64 v[96:97], v[96:97], 0, v[130:131]
	v_max_f32_e32 v92, 0, v92
	v_max_f32_e32 v93, 0, v93
	v_max_f32_e32 v94, 0, v94
	v_max_f32_e32 v95, v95, v95
	v_lshl_add_u64 v[96:97], v[96:97], 0, v[134:135]
	v_max_f32_e32 v95, 0, v95
	v_mul_f32_e32 v92, v92, v92
	v_mul_f32_e32 v93, v93, v93
	v_mul_f32_e32 v94, v94, v94
	v_max_f32_e32 v88, v88, v88
	v_max_f32_e32 v89, v89, v89
	v_max_f32_e32 v84, v84, v84
	v_max_f32_e32 v85, v85, v85
	v_max_f32_e32 v80, v80, v80
	v_max_f32_e32 v81, v81, v81
	v_max_f32_e32 v76, v76, v76
	v_max_f32_e32 v77, v77, v77
	v_max_f32_e32 v72, v72, v72
	v_max_f32_e32 v73, v73, v73
	v_max_f32_e32 v68, v68, v68
	v_max_f32_e32 v69, v69, v69
	v_max_f32_e32 v64, v64, v64
	v_mul_f32_e32 v95, v95, v95
	v_cvt_pk_bf16_f32 v92, v92, v93
	v_cvt_pk_bf16_f32 v93, v94, v95
	v_max_f32_e32 v88, 0, v88
	v_max_f32_e32 v89, 0, v89
	v_max_f32_e32 v90, v90, v90
	v_max_f32_e32 v91, v91, v91
	v_max_f32_e32 v84, 0, v84
	v_max_f32_e32 v85, 0, v85
	v_max_f32_e32 v86, v86, v86
	v_max_f32_e32 v87, v87, v87
	v_max_f32_e32 v80, 0, v80
	v_max_f32_e32 v81, 0, v81
	v_max_f32_e32 v82, v82, v82
	v_max_f32_e32 v83, v83, v83
	v_max_f32_e32 v76, 0, v76
	v_max_f32_e32 v77, 0, v77
	v_max_f32_e32 v78, v78, v78
	v_max_f32_e32 v79, v79, v79
	v_max_f32_e32 v72, 0, v72
	v_max_f32_e32 v73, 0, v73
	v_max_f32_e32 v74, v74, v74
	v_max_f32_e32 v75, v75, v75
	v_max_f32_e32 v68, 0, v68
	v_max_f32_e32 v69, 0, v69
	v_max_f32_e32 v70, v70, v70
	v_max_f32_e32 v71, v71, v71
	v_max_f32_e32 v64, 0, v64
	v_max_f32_e32 v65, v65, v65
	v_lshl_add_u64 v[98:99], v[96:97], 0, s[22:23]
	v_lshl_add_u64 v[98:99], v[98:99], 0, v[254:255]
	v_max_f32_e32 v90, 0, v90
	v_max_f32_e32 v91, 0, v91
	v_mul_f32_e32 v88, v88, v88
	v_mul_f32_e32 v89, v89, v89
	v_max_f32_e32 v86, 0, v86
	v_max_f32_e32 v87, 0, v87
	v_mul_f32_e32 v84, v84, v84
	v_mul_f32_e32 v85, v85, v85
	v_max_f32_e32 v82, 0, v82
	v_max_f32_e32 v83, 0, v83
	v_mul_f32_e32 v80, v80, v80
	v_mul_f32_e32 v81, v81, v81
	v_max_f32_e32 v78, 0, v78
	v_max_f32_e32 v79, 0, v79
	v_mul_f32_e32 v76, v76, v76
	v_mul_f32_e32 v77, v77, v77
	v_max_f32_e32 v74, 0, v74
	v_max_f32_e32 v75, 0, v75
	v_mul_f32_e32 v72, v72, v72
	v_mul_f32_e32 v73, v73, v73
	v_max_f32_e32 v70, 0, v70
	v_max_f32_e32 v71, 0, v71
	v_mul_f32_e32 v68, v68, v68
	v_mul_f32_e32 v69, v69, v69
	v_max_f32_e32 v65, 0, v65
	v_max_f32_e32 v66, v66, v66
	v_max_f32_e32 v67, v67, v67
	v_mul_f32_e32 v64, v64, v64
	v_mul_f32_e32 v90, v90, v90
	v_mul_f32_e32 v91, v91, v91
	v_cvt_pk_bf16_f32 v94, v88, v89
	v_cvt_pk_bf16_f32 v95, v90, v91
	s_nop 1
	v_permlane16_swap_b32_e32 v92, v94
	v_permlane16_swap_b32_e32 v93, v95
	global_store_dwordx4 v[98:99], v[92:95], off
	s_nop 1
	v_mul_f32_e32 v86, v86, v86
	v_mul_f32_e32 v87, v87, v87
	v_cvt_pk_bf16_f32 v84, v84, v85
	v_cvt_pk_bf16_f32 v85, v86, v87
	v_mul_f32_e32 v82, v82, v82
	v_mul_f32_e32 v83, v83, v83
	v_cvt_pk_bf16_f32 v86, v80, v81
	v_cvt_pk_bf16_f32 v87, v82, v83
	s_nop 1
	v_permlane16_swap_b32_e32 v84, v86
	v_permlane16_swap_b32_e32 v85, v87
	global_store_dwordx4 v[98:99], v[84:87], off offset:64
	s_nop 1
	v_mul_f32_e32 v78, v78, v78
	v_mul_f32_e32 v79, v79, v79
	v_cvt_pk_bf16_f32 v76, v76, v77
	v_cvt_pk_bf16_f32 v77, v78, v79
	v_mul_f32_e32 v74, v74, v74
	v_mul_f32_e32 v75, v75, v75
	v_cvt_pk_bf16_f32 v78, v72, v73
	v_cvt_pk_bf16_f32 v79, v74, v75
	s_nop 1
	v_permlane16_swap_b32_e32 v76, v78
	v_permlane16_swap_b32_e32 v77, v79
	global_store_dwordx4 v[98:99], v[76:79], off offset:128
	s_nop 1
	v_mul_f32_e32 v70, v70, v70
	v_mul_f32_e32 v71, v71, v71
	v_cvt_pk_bf16_f32 v68, v68, v69
	v_cvt_pk_bf16_f32 v69, v70, v71
	v_max_f32_e32 v66, 0, v66
	v_max_f32_e32 v67, 0, v67
	v_mul_f32_e32 v65, v65, v65
	v_cvt_pk_bf16_f32 v70, v64, v65
	v_mul_f32_e32 v66, v66, v66
	v_mul_f32_e32 v67, v67, v67
	v_cvt_pk_bf16_f32 v71, v66, v67
	s_nop 1
	v_permlane16_swap_b32_e32 v68, v70
	v_permlane16_swap_b32_e32 v69, v71
	global_store_dwordx4 v[98:99], v[68:71], off offset:192
	s_nop 1
	v_or_b32_e32 v64, 32, v128
	v_ashrrev_i32_e32 v65, 31, v64
	v_mov_b64_e32 v[66:67], v[132:133]
	v_lshlrev_b64 v[64:65], 13, v[64:65]
	v_max_f32_e32 v60, v60, v60
	v_lshl_add_u64 v[64:65], v[66:67], 0, v[64:65]
	v_max_f32_e32 v61, v61, v61
	v_max_f32_e32 v62, v62, v62
	v_lshl_add_u64 v[64:65], v[64:65], 0, v[130:131]
	v_max_f32_e32 v60, 0, v60
	v_max_f32_e32 v61, 0, v61
	v_max_f32_e32 v62, 0, v62
	v_max_f32_e32 v63, v63, v63
	v_lshl_add_u64 v[64:65], v[64:65], 0, v[134:135]
	v_max_f32_e32 v63, 0, v63
	v_mul_f32_e32 v60, v60, v60
	v_mul_f32_e32 v61, v61, v61
	v_mul_f32_e32 v62, v62, v62
	v_max_f32_e32 v56, v56, v56
	v_max_f32_e32 v57, v57, v57
	v_max_f32_e32 v52, v52, v52
	v_max_f32_e32 v53, v53, v53
	v_max_f32_e32 v48, v48, v48
	v_max_f32_e32 v49, v49, v49
	v_max_f32_e32 v44, v44, v44
	v_max_f32_e32 v45, v45, v45
	v_max_f32_e32 v40, v40, v40
	v_max_f32_e32 v41, v41, v41
	v_max_f32_e32 v36, v36, v36
	v_max_f32_e32 v37, v37, v37
	v_max_f32_e32 v32, v32, v32
	v_mul_f32_e32 v63, v63, v63
	v_cvt_pk_bf16_f32 v60, v60, v61
	v_cvt_pk_bf16_f32 v61, v62, v63
	v_max_f32_e32 v56, 0, v56
	v_max_f32_e32 v57, 0, v57
	v_max_f32_e32 v58, v58, v58
	v_max_f32_e32 v59, v59, v59
	v_max_f32_e32 v52, 0, v52
	v_max_f32_e32 v53, 0, v53
	v_max_f32_e32 v54, v54, v54
	v_max_f32_e32 v55, v55, v55
	v_max_f32_e32 v48, 0, v48
	v_max_f32_e32 v49, 0, v49
	v_max_f32_e32 v50, v50, v50
	v_max_f32_e32 v51, v51, v51
	v_max_f32_e32 v44, 0, v44
	v_max_f32_e32 v45, 0, v45
	v_max_f32_e32 v46, v46, v46
	v_max_f32_e32 v47, v47, v47
	v_max_f32_e32 v40, 0, v40
	v_max_f32_e32 v41, 0, v41
	v_max_f32_e32 v42, v42, v42
	v_max_f32_e32 v43, v43, v43
	v_max_f32_e32 v36, 0, v36
	v_max_f32_e32 v37, 0, v37
	v_max_f32_e32 v38, v38, v38
	v_max_f32_e32 v39, v39, v39
	v_max_f32_e32 v32, 0, v32
	v_max_f32_e32 v33, v33, v33
	v_lshl_add_u64 v[66:67], v[64:65], 0, s[22:23]
	v_lshl_add_u64 v[66:67], v[66:67], 0, v[254:255]
	v_max_f32_e32 v58, 0, v58
	v_max_f32_e32 v59, 0, v59
	v_mul_f32_e32 v56, v56, v56
	v_mul_f32_e32 v57, v57, v57
	v_max_f32_e32 v54, 0, v54
	v_max_f32_e32 v55, 0, v55
	v_mul_f32_e32 v52, v52, v52
	v_mul_f32_e32 v53, v53, v53
	v_max_f32_e32 v50, 0, v50
	v_max_f32_e32 v51, 0, v51
	v_mul_f32_e32 v48, v48, v48
	v_mul_f32_e32 v49, v49, v49
	v_max_f32_e32 v46, 0, v46
	v_max_f32_e32 v47, 0, v47
	v_mul_f32_e32 v44, v44, v44
	v_mul_f32_e32 v45, v45, v45
	v_max_f32_e32 v42, 0, v42
	v_max_f32_e32 v43, 0, v43
	v_mul_f32_e32 v40, v40, v40
	v_mul_f32_e32 v41, v41, v41
	v_max_f32_e32 v38, 0, v38
	v_max_f32_e32 v39, 0, v39
	v_mul_f32_e32 v36, v36, v36
	v_mul_f32_e32 v37, v37, v37
	v_max_f32_e32 v33, 0, v33
	v_max_f32_e32 v34, v34, v34
	v_max_f32_e32 v35, v35, v35
	v_mul_f32_e32 v32, v32, v32
	v_mul_f32_e32 v58, v58, v58
	v_mul_f32_e32 v59, v59, v59
	v_cvt_pk_bf16_f32 v62, v56, v57
	v_cvt_pk_bf16_f32 v63, v58, v59
	s_nop 1
	v_permlane16_swap_b32_e32 v60, v62
	v_permlane16_swap_b32_e32 v61, v63
	global_store_dwordx4 v[66:67], v[60:63], off
	s_nop 1
	v_mul_f32_e32 v54, v54, v54
	v_mul_f32_e32 v55, v55, v55
	v_cvt_pk_bf16_f32 v52, v52, v53
	v_cvt_pk_bf16_f32 v53, v54, v55
	v_mul_f32_e32 v50, v50, v50
	v_mul_f32_e32 v51, v51, v51
	v_cvt_pk_bf16_f32 v54, v48, v49
	v_cvt_pk_bf16_f32 v55, v50, v51
	s_nop 1
	v_permlane16_swap_b32_e32 v52, v54
	v_permlane16_swap_b32_e32 v53, v55
	global_store_dwordx4 v[66:67], v[52:55], off offset:64
	s_nop 1
	v_mul_f32_e32 v46, v46, v46
	v_mul_f32_e32 v47, v47, v47
	v_cvt_pk_bf16_f32 v44, v44, v45
	v_cvt_pk_bf16_f32 v45, v46, v47
	v_mul_f32_e32 v42, v42, v42
	v_mul_f32_e32 v43, v43, v43
	v_cvt_pk_bf16_f32 v46, v40, v41
	v_cvt_pk_bf16_f32 v47, v42, v43
	s_nop 1
	v_permlane16_swap_b32_e32 v44, v46
	v_permlane16_swap_b32_e32 v45, v47
	global_store_dwordx4 v[66:67], v[44:47], off offset:128
	s_nop 1
	v_mul_f32_e32 v38, v38, v38
	v_mul_f32_e32 v39, v39, v39
	v_cvt_pk_bf16_f32 v36, v36, v37
	v_cvt_pk_bf16_f32 v37, v38, v39
	v_max_f32_e32 v34, 0, v34
	v_max_f32_e32 v35, 0, v35
	v_mul_f32_e32 v33, v33, v33
	v_cvt_pk_bf16_f32 v38, v32, v33
	v_mul_f32_e32 v34, v34, v34
	v_mul_f32_e32 v35, v35, v35
	v_cvt_pk_bf16_f32 v39, v34, v35
	s_nop 1
	v_permlane16_swap_b32_e32 v36, v38
	v_permlane16_swap_b32_e32 v37, v39
	global_store_dwordx4 v[66:67], v[36:39], off offset:192
	s_nop 1
	v_or_b32_e32 v32, 48, v128
	v_ashrrev_i32_e32 v33, 31, v32
	v_mov_b64_e32 v[34:35], v[132:133]
	v_lshlrev_b64 v[32:33], 13, v[32:33]
	v_max_f32_e32 v28, v28, v28
	v_lshl_add_u64 v[32:33], v[34:35], 0, v[32:33]
	v_max_f32_e32 v29, v29, v29
	v_max_f32_e32 v30, v30, v30
	v_lshl_add_u64 v[32:33], v[32:33], 0, v[130:131]
	v_max_f32_e32 v28, 0, v28
	v_max_f32_e32 v29, 0, v29
	v_max_f32_e32 v30, 0, v30
	v_max_f32_e32 v31, v31, v31
	v_lshl_add_u64 v[32:33], v[32:33], 0, v[134:135]
	v_max_f32_e32 v31, 0, v31
	v_mul_f32_e32 v28, v28, v28
	v_mul_f32_e32 v29, v29, v29
	v_mul_f32_e32 v30, v30, v30
	v_max_f32_e32 v24, v24, v24
	v_max_f32_e32 v25, v25, v25
	v_max_f32_e32 v20, v20, v20
	v_max_f32_e32 v21, v21, v21
	v_max_f32_e32 v16, v16, v16
	v_max_f32_e32 v17, v17, v17
	v_max_f32_e32 v12, v12, v12
	v_max_f32_e32 v13, v13, v13
	v_max_f32_e32 v8, v8, v8
	v_max_f32_e32 v9, v9, v9
	v_max_f32_e32 v4, v4, v4
	v_max_f32_e32 v5, v5, v5
	v_max_f32_e32 v0, v0, v0
	v_max_f32_e32 v1, v1, v1
	v_mul_f32_e32 v31, v31, v31
	v_cvt_pk_bf16_f32 v28, v28, v29
	v_cvt_pk_bf16_f32 v29, v30, v31
	v_max_f32_e32 v24, 0, v24
	v_max_f32_e32 v25, 0, v25
	v_max_f32_e32 v26, v26, v26
	v_max_f32_e32 v27, v27, v27
	v_max_f32_e32 v20, 0, v20
	v_max_f32_e32 v21, 0, v21
	v_max_f32_e32 v22, v22, v22
	v_max_f32_e32 v23, v23, v23
	v_max_f32_e32 v16, 0, v16
	v_max_f32_e32 v17, 0, v17
	v_max_f32_e32 v18, v18, v18
	v_max_f32_e32 v19, v19, v19
	v_max_f32_e32 v12, 0, v12
	v_max_f32_e32 v13, 0, v13
	v_max_f32_e32 v14, v14, v14
	v_max_f32_e32 v15, v15, v15
	v_max_f32_e32 v8, 0, v8
	v_max_f32_e32 v9, 0, v9
	v_max_f32_e32 v10, v10, v10
	v_max_f32_e32 v11, v11, v11
	v_max_f32_e32 v4, 0, v4
	v_max_f32_e32 v5, 0, v5
	v_max_f32_e32 v6, v6, v6
	v_max_f32_e32 v7, v7, v7
	v_max_f32_e32 v0, 0, v0
	v_max_f32_e32 v1, 0, v1
	v_max_f32_e32 v2, v2, v2
	v_max_f32_e32 v3, v3, v3
	v_lshl_add_u64 v[34:35], v[32:33], 0, s[22:23]
	v_lshl_add_u64 v[34:35], v[34:35], 0, v[254:255]
	v_max_f32_e32 v26, 0, v26
	v_max_f32_e32 v27, 0, v27
	v_mul_f32_e32 v24, v24, v24
	v_mul_f32_e32 v25, v25, v25
	v_max_f32_e32 v22, 0, v22
	v_max_f32_e32 v23, 0, v23
	v_mul_f32_e32 v20, v20, v20
	v_mul_f32_e32 v21, v21, v21
	v_max_f32_e32 v18, 0, v18
	v_max_f32_e32 v19, 0, v19
	v_mul_f32_e32 v16, v16, v16
	v_mul_f32_e32 v17, v17, v17
	v_max_f32_e32 v14, 0, v14
	v_max_f32_e32 v15, 0, v15
	v_mul_f32_e32 v12, v12, v12
	v_mul_f32_e32 v13, v13, v13
	v_max_f32_e32 v10, 0, v10
	v_max_f32_e32 v11, 0, v11
	v_mul_f32_e32 v8, v8, v8
	v_mul_f32_e32 v9, v9, v9
	v_max_f32_e32 v6, 0, v6
	v_max_f32_e32 v7, 0, v7
	v_mul_f32_e32 v4, v4, v4
	v_mul_f32_e32 v5, v5, v5
	v_max_f32_e32 v2, 0, v2
	v_max_f32_e32 v3, 0, v3
	v_mul_f32_e32 v0, v0, v0
	v_mul_f32_e32 v1, v1, v1
	s_add_i32 s15, s15, 1
	s_mov_b64 s[4:5], 0
	v_mul_f32_e32 v26, v26, v26
	v_mul_f32_e32 v27, v27, v27
	v_cvt_pk_bf16_f32 v30, v24, v25
	v_cvt_pk_bf16_f32 v31, v26, v27
	s_nop 1
	v_permlane16_swap_b32_e32 v28, v30
	v_permlane16_swap_b32_e32 v29, v31
	global_store_dwordx4 v[34:35], v[28:31], off
	s_nop 1
	v_mul_f32_e32 v22, v22, v22
	v_mul_f32_e32 v23, v23, v23
	v_cvt_pk_bf16_f32 v20, v20, v21
	v_cvt_pk_bf16_f32 v21, v22, v23
	v_mul_f32_e32 v18, v18, v18
	v_mul_f32_e32 v19, v19, v19
	v_cvt_pk_bf16_f32 v22, v16, v17
	v_cvt_pk_bf16_f32 v23, v18, v19
	s_nop 1
	v_permlane16_swap_b32_e32 v20, v22
	v_permlane16_swap_b32_e32 v21, v23
	global_store_dwordx4 v[34:35], v[20:23], off offset:64
	s_nop 1
	v_mul_f32_e32 v14, v14, v14
	v_mul_f32_e32 v15, v15, v15
	v_cvt_pk_bf16_f32 v12, v12, v13
	v_cvt_pk_bf16_f32 v13, v14, v15
	v_mul_f32_e32 v10, v10, v10
	v_mul_f32_e32 v11, v11, v11
	v_cvt_pk_bf16_f32 v14, v8, v9
	v_cvt_pk_bf16_f32 v15, v10, v11
	s_nop 1
	v_permlane16_swap_b32_e32 v12, v14
	v_permlane16_swap_b32_e32 v13, v15
	global_store_dwordx4 v[34:35], v[12:15], off offset:128
	s_nop 1
	v_mul_f32_e32 v6, v6, v6
	v_mul_f32_e32 v7, v7, v7
	v_cvt_pk_bf16_f32 v4, v4, v5
	v_cvt_pk_bf16_f32 v5, v6, v7
	v_mul_f32_e32 v2, v2, v2
	v_mul_f32_e32 v3, v3, v3
	v_cvt_pk_bf16_f32 v6, v0, v1
	v_cvt_pk_bf16_f32 v7, v2, v3
	s_nop 1
	v_permlane16_swap_b32_e32 v4, v6
	v_permlane16_swap_b32_e32 v5, v7
	global_store_dwordx4 v[34:35], v[4:7], off offset:192
	s_nop 1

	.amdhsa_kernel _Z14fwd_megakernel6Params
		.amdhsa_group_segment_fixed_size 0
		.amdhsa_private_segment_fixed_size 0
		.amdhsa_kernarg_size 616
		.amdhsa_user_sgpr_count 2
		.amdhsa_user_sgpr_dispatch_ptr 0
		.amdhsa_user_sgpr_queue_ptr 0
		.amdhsa_user_sgpr_kernarg_segment_ptr 1
		.amdhsa_user_sgpr_dispatch_id 0
		.amdhsa_user_sgpr_kernarg_preload_length 0
		.amdhsa_user_sgpr_kernarg_preload_offset 0
		.amdhsa_user_sgpr_private_segment_size 0
		.amdhsa_uses_dynamic_stack 0
		.amdhsa_enable_private_segment 0
		.amdhsa_system_sgpr_workgroup_id_x 1
		.amdhsa_system_sgpr_workgroup_id_y 0
		.amdhsa_system_sgpr_workgroup_id_z 0
		.amdhsa_system_sgpr_workgroup_info 0
		.amdhsa_system_vgpr_workitem_id 2
		.amdhsa_next_free_vgpr 256
		.amdhsa_next_free_sgpr 102
		.amdhsa_accum_offset 256
		.amdhsa_reserve_vcc 1
		.amdhsa_float_round_mode_32 0
		.amdhsa_float_round_mode_16_64 0
		.amdhsa_float_denorm_mode_32 3
		.amdhsa_float_denorm_mode_16_64 3
		.amdhsa_dx10_clamp 1
		.amdhsa_ieee_mode 1
		.amdhsa_fp16_overflow 0
		.amdhsa_tg_split 0
		.amdhsa_exception_fp_ieee_invalid_op 0
		.amdhsa_exception_fp_denorm_src 0
		.amdhsa_exception_fp_ieee_div_zero 0
		.amdhsa_exception_fp_ieee_overflow 0
		.amdhsa_exception_fp_ieee_underflow 0
		.amdhsa_exception_fp_ieee_inexact 0
		.amdhsa_exception_int_div_zero 0
	.end_amdhsa_kernel

amdhsa.kernels:
  - .agpr_count:     0
    .args:
      - .offset:         0
        .size:           360
        .value_kind:     by_value
      - .offset:         360
        .size:           4
        .value_kind:     hidden_block_count_x
      - .offset:         364
        .size:           4
        .value_kind:     hidden_block_count_y
      - .offset:         368
        .size:           4
        .value_kind:     hidden_block_count_z
      - .offset:         372
        .size:           2
        .value_kind:     hidden_group_size_x
      - .offset:         374
        .size:           2
        .value_kind:     hidden_group_size_y
      - .offset:         376
        .size:           2
        .value_kind:     hidden_group_size_z
      - .offset:         378
        .size:           2
        .value_kind:     hidden_remainder_x
      - .offset:         380
        .size:           2
        .value_kind:     hidden_remainder_y
      - .offset:         382
        .size:           2
        .value_kind:     hidden_remainder_z
      - .offset:         400
        .size:           8
        .value_kind:     hidden_global_offset_x
      - .offset:         408
        .size:           8
        .value_kind:     hidden_global_offset_y
      - .offset:         416
        .size:           8
        .value_kind:     hidden_global_offset_z
      - .offset:         424
        .size:           2
        .value_kind:     hidden_grid_dims
      - .offset:         448
        .size:           8
        .value_kind:     hidden_multigrid_sync_arg
      - .offset:         480
        .size:           4
        .value_kind:     hidden_dynamic_lds_size
    .group_segment_fixed_size: 0
    .kernarg_segment_align: 8
    .kernarg_segment_size: 616
    .language:       OpenCL C
    .language_version:
      - 2
      - 0
    .max_flat_workgroup_size: 512
    .name:           _Z14fwd_megakernel6Params
    .private_segment_fixed_size: 0
    .sgpr_count:     108
    .sgpr_spill_count: 95
    .symbol:         _Z14fwd_megakernel6Params.kd
    .uniform_work_group_size: 1
    .uses_dynamic_stack: false
    .vgpr_count:     256
    .vgpr_spill_count: 0
    .wavefront_size: 64
